# seam inv overlapped with arrival atomic; FFN-up and w_in K-loop first trip peeled (no acc zeroing, no vmcnt0 in w_in loop); lead-half align barrier moved into SwiGLU epilogue
# speedup vs baseline: 1.0110x; 1.0110x over previous
.LBB0_355:
	s_or_b64 exec, exec, s[40:41]
	buffer_inv sc1
	s_waitcnt vmcnt(0)
	v_readfirstlane_b32 s4, v2
	s_nop 1
	v_add_u32_e32 v0, s4, v0
	v_and_b32_e32 v2, -4, v0
	v_and_b32_e32 v0, 3, v0
	v_cmp_eq_u32_e64 s[4:5], 3, v0
	v_add_u32_e32 v2, 4, v2
	s_and_b64 s[4:5], s[4:5], exec

.LBB0_444:
	s_add_u32 s48, s46, 0x20080
	s_addc_u32 s49, s47, 0
	s_add_u32 s25, s50, 0x100
	s_addc_u32 s64, s51, 0
	s_mov_b32 s65, -2
	s_add_u32 s46, s48, 0xfffe0080
	s_addc_u32 s47, s49, -1
	s_add_i32 s84, 0, 0x10000
	s_cmp_eq_u32 s65, 4
	s_cselect_b32 s47, s15, s47
	s_cselect_b32 s46, s14, s46
	v_add_u32_e32 v0, s84, v147
	s_cselect_b32 s51, s17, s64
	s_cselect_b32 s50, s16, s25
	s_add_i32 s86, 0, 0x14000
	ds_read_b128 v[150:153], v0
	ds_read_b128 v[154:157], v0 offset:1024
	ds_read_b128 v[158:161], v0 offset:2048
	ds_read_b128 v[162:165], v0 offset:3072
	v_add_u32_e32 v0, s86, v147
	ds_read_b128 v[166:169], v0
	ds_read_b128 v[170:173], v0 offset:1024
	ds_read_b128 v[174:177], v0 offset:2048
	ds_read_b128 v[178:181], v0 offset:3072
	v_mov_b32_e32 v0, v132
	ds_read_b128 v[182:185], v148
	ds_read_b128 v[186:189], v148 offset:1024
	ds_read_b128 v[190:193], v148 offset:2048
	ds_read_b128 v[194:197], v148 offset:3072
	ds_read_b128 v[198:201], v148 offset:4096
	ds_read_b128 v[202:205], v148 offset:5120
	ds_read_b128 v[206:209], v148 offset:6144
	ds_read_b128 v[210:213], v148 offset:7168
	s_add_i32 m0, s59, 0xc000
	s_nop 0
	global_load_lds_dwordx4 v0, s[48:49]
	v_mov_b32_e32 v0, v133
	s_add_i32 m0, s59, 0xe000
	s_nop 0
	global_load_lds_dwordx4 v0, s[48:49]
	s_waitcnt vmcnt(8)
	s_waitcnt lgkmcnt(0)
	s_barrier
	s_setprio 1
	s_waitcnt lgkmcnt(0)
	v_mfma_i32_16x16x64_i8 v[126:129], v[150:153], v[182:185], 0
	v_mfma_i32_16x16x64_i8 v[122:125], v[158:161], v[182:185], 0
	v_mfma_i32_16x16x64_i8 v[110:113], v[150:153], v[190:193], 0
	v_mfma_i32_16x16x64_i8 v[106:109], v[158:161], v[190:193], 0
	v_mfma_i32_16x16x64_i8 v[94:97], v[150:153], v[198:201], 0
	v_mfma_i32_16x16x64_i8 v[90:93], v[158:161], v[198:201], 0
	v_mfma_i32_16x16x64_i8 v[78:81], v[150:153], v[206:209], 0
	v_mfma_i32_16x16x64_i8 v[74:77], v[158:161], v[206:209], 0
	v_mfma_i32_16x16x64_i8 v[126:129], v[154:157], v[186:189], v[126:129]
	v_mfma_i32_16x16x64_i8 v[122:125], v[162:165], v[186:189], v[122:125]
	v_mfma_i32_16x16x64_i8 v[110:113], v[154:157], v[194:197], v[110:113]
	v_mfma_i32_16x16x64_i8 v[106:109], v[162:165], v[194:197], v[106:109]
	v_mfma_i32_16x16x64_i8 v[94:97], v[154:157], v[202:205], v[94:97]
	v_mfma_i32_16x16x64_i8 v[90:93], v[162:165], v[202:205], v[90:93]
	v_mfma_i32_16x16x64_i8 v[78:81], v[154:157], v[210:213], v[78:81]
	v_mfma_i32_16x16x64_i8 v[74:77], v[162:165], v[210:213], v[74:77]
	s_setprio 0
	s_setprio 1
	v_mfma_i32_16x16x64_i8 v[118:121], v[166:169], v[182:185], 0
	v_mfma_i32_16x16x64_i8 v[114:117], v[174:177], v[182:185], 0
	v_mfma_i32_16x16x64_i8 v[102:105], v[166:169], v[190:193], 0
	v_mfma_i32_16x16x64_i8 v[98:101], v[174:177], v[190:193], 0
	v_mfma_i32_16x16x64_i8 v[86:89], v[166:169], v[198:201], 0
	v_mfma_i32_16x16x64_i8 v[82:85], v[174:177], v[198:201], 0
	v_mfma_i32_16x16x64_i8 v[70:73], v[166:169], v[206:209], 0
	v_mfma_i32_16x16x64_i8 v[66:69], v[174:177], v[206:209], 0
	v_mfma_i32_16x16x64_i8 v[118:121], v[170:173], v[186:189], v[118:121]
	v_mfma_i32_16x16x64_i8 v[114:117], v[178:181], v[186:189], v[114:117]
	v_mfma_i32_16x16x64_i8 v[102:105], v[170:173], v[194:197], v[102:105]
	v_mfma_i32_16x16x64_i8 v[98:101], v[178:181], v[194:197], v[98:101]
	v_mfma_i32_16x16x64_i8 v[86:89], v[170:173], v[202:205], v[86:89]
	v_mfma_i32_16x16x64_i8 v[82:85], v[178:181], v[202:205], v[82:85]
	v_mfma_i32_16x16x64_i8 v[70:73], v[170:173], v[210:213], v[70:73]
	v_mfma_i32_16x16x64_i8 v[66:69], v[178:181], v[210:213], v[66:69]
	s_setprio 0
	s_barrier
	v_mov_b32_e32 v0, v143
	s_add_i32 s84, s84, s40
	ds_read_b128 v[182:185], v148 offset:16384
	ds_read_b128 v[186:189], v148 offset:17408
	ds_read_b128 v[190:193], v148 offset:18432
	ds_read_b128 v[194:197], v148 offset:19456
	ds_read_b128 v[198:201], v148 offset:20480
	ds_read_b128 v[202:205], v148 offset:21504
	ds_read_b128 v[206:209], v148 offset:22528
	ds_read_b128 v[210:213], v148 offset:23552
	s_mov_b32 m0, s84
	s_nop 0
	global_load_lds_dwordx4 v0, s[50:51]
	v_mov_b32_e32 v0, v144
	s_add_i32 m0, s84, 0x2000
	s_add_u32 s84, s50, 0x20000
	global_load_lds_dwordx4 v0, s[50:51]
	s_addc_u32 s85, s51, 0
	v_mov_b32_e32 v0, v143
	s_add_i32 s86, s86, s40
	s_mov_b32 m0, s86
	s_nop 0
	global_load_lds_dwordx4 v0, s[84:85]
	v_mov_b32_e32 v0, v144
	s_add_i32 m0, s86, 0x2000
	s_nop 0
	global_load_lds_dwordx4 v0, s[84:85]
	v_mov_b32_e32 v0, v132
	s_mov_b32 m0, s59
	s_nop 0
	global_load_lds_dwordx4 v0, s[46:47]
	v_mov_b32_e32 v0, v133
	s_mov_b32 m0, s60
	s_nop 0
	global_load_lds_dwordx4 v0, s[46:47]
	s_waitcnt vmcnt(8)
	s_waitcnt lgkmcnt(0)
	s_barrier
	s_setprio 1
	s_waitcnt lgkmcnt(0)
	v_mfma_i32_16x16x64_i8 v[62:65], v[150:153], v[182:185], 0
	v_mfma_i32_16x16x64_i8 v[58:61], v[158:161], v[182:185], 0
	v_mfma_i32_16x16x64_i8 v[46:49], v[150:153], v[190:193], 0
	v_mfma_i32_16x16x64_i8 v[42:45], v[158:161], v[190:193], 0
	v_mfma_i32_16x16x64_i8 v[30:33], v[150:153], v[198:201], 0
	v_mfma_i32_16x16x64_i8 v[26:29], v[158:161], v[198:201], 0
	v_mfma_i32_16x16x64_i8 v[14:17], v[150:153], v[206:209], 0
	v_mfma_i32_16x16x64_i8 v[10:13], v[158:161], v[206:209], 0
	v_mfma_i32_16x16x64_i8 v[62:65], v[154:157], v[186:189], v[62:65]
	v_mfma_i32_16x16x64_i8 v[58:61], v[162:165], v[186:189], v[58:61]
	v_mfma_i32_16x16x64_i8 v[46:49], v[154:157], v[194:197], v[46:49]
	v_mfma_i32_16x16x64_i8 v[42:45], v[162:165], v[194:197], v[42:45]
	v_mfma_i32_16x16x64_i8 v[30:33], v[154:157], v[202:205], v[30:33]
	v_mfma_i32_16x16x64_i8 v[26:29], v[162:165], v[202:205], v[26:29]
	v_mfma_i32_16x16x64_i8 v[14:17], v[154:157], v[210:213], v[14:17]
	v_mfma_i32_16x16x64_i8 v[10:13], v[162:165], v[210:213], v[10:13]
	s_setprio 0
	s_setprio 1
	v_mfma_i32_16x16x64_i8 v[54:57], v[166:169], v[182:185], 0
	v_mfma_i32_16x16x64_i8 v[50:53], v[174:177], v[182:185], 0
	v_mfma_i32_16x16x64_i8 v[38:41], v[166:169], v[190:193], 0
	v_mfma_i32_16x16x64_i8 v[34:37], v[174:177], v[190:193], 0
	v_mfma_i32_16x16x64_i8 v[22:25], v[166:169], v[198:201], 0
	v_mfma_i32_16x16x64_i8 v[18:21], v[174:177], v[198:201], 0
	v_mfma_i32_16x16x64_i8 v[6:9], v[166:169], v[206:209], 0
	v_mfma_i32_16x16x64_i8 v[2:5], v[174:177], v[206:209], 0
	v_mfma_i32_16x16x64_i8 v[54:57], v[170:173], v[186:189], v[54:57]
	v_mfma_i32_16x16x64_i8 v[50:53], v[178:181], v[186:189], v[50:53]
	v_mfma_i32_16x16x64_i8 v[38:41], v[170:173], v[194:197], v[38:41]
	v_mfma_i32_16x16x64_i8 v[34:37], v[178:181], v[194:197], v[34:37]
	v_mfma_i32_16x16x64_i8 v[22:25], v[170:173], v[202:205], v[22:25]
	v_mfma_i32_16x16x64_i8 v[18:21], v[178:181], v[202:205], v[18:21]
	v_mfma_i32_16x16x64_i8 v[6:9], v[170:173], v[210:213], v[6:9]
	v_mfma_i32_16x16x64_i8 v[2:5], v[178:181], v[210:213], v[2:5]
	s_setprio 0
	s_barrier
	s_add_i32 s86, 0, 0x18000
	v_add_u32_e32 v0, s86, v147
	s_add_i32 s87, 0, 0x1c000
	ds_read_b128 v[150:153], v0
	ds_read_b128 v[154:157], v0 offset:1024
	ds_read_b128 v[158:161], v0 offset:2048
	ds_read_b128 v[162:165], v0 offset:3072
	v_add_u32_e32 v0, s87, v147
	ds_read_b128 v[166:169], v0
	ds_read_b128 v[170:173], v0 offset:1024
	ds_read_b128 v[174:177], v0 offset:2048
	ds_read_b128 v[178:181], v0 offset:3072
	s_add_u32 s84, s46, 0x20000
	v_mov_b32_e32 v0, v132
	s_mov_b32 m0, s61
	ds_read_b128 v[182:185], v148 offset:32768
	ds_read_b128 v[186:189], v148 offset:33792
	ds_read_b128 v[190:193], v148 offset:34816
	ds_read_b128 v[194:197], v148 offset:35840
	ds_read_b128 v[198:201], v148 offset:36864
	ds_read_b128 v[202:205], v148 offset:37888
	ds_read_b128 v[206:209], v148 offset:38912
	ds_read_b128 v[210:213], v148 offset:39936
	s_addc_u32 s85, s47, 0
	s_nop 0
	global_load_lds_dwordx4 v0, s[84:85]
	v_mov_b32_e32 v0, v133
	s_mov_b32 m0, s66
	s_nop 0
	global_load_lds_dwordx4 v0, s[84:85]
	s_waitcnt vmcnt(8)
	s_waitcnt lgkmcnt(0)
	s_barrier
	s_setprio 1
	s_waitcnt lgkmcnt(0)
	v_mfma_i32_16x16x64_i8 v[126:129], v[150:153], v[182:185], v[126:129]
	v_mfma_i32_16x16x64_i8 v[122:125], v[158:161], v[182:185], v[122:125]
	v_mfma_i32_16x16x64_i8 v[110:113], v[150:153], v[190:193], v[110:113]
	v_mfma_i32_16x16x64_i8 v[106:109], v[158:161], v[190:193], v[106:109]
	v_mfma_i32_16x16x64_i8 v[94:97], v[150:153], v[198:201], v[94:97]
	v_mfma_i32_16x16x64_i8 v[90:93], v[158:161], v[198:201], v[90:93]
	v_mfma_i32_16x16x64_i8 v[78:81], v[150:153], v[206:209], v[78:81]
	v_mfma_i32_16x16x64_i8 v[74:77], v[158:161], v[206:209], v[74:77]
	v_mfma_i32_16x16x64_i8 v[126:129], v[154:157], v[186:189], v[126:129]
	v_mfma_i32_16x16x64_i8 v[122:125], v[162:165], v[186:189], v[122:125]
	v_mfma_i32_16x16x64_i8 v[110:113], v[154:157], v[194:197], v[110:113]
	v_mfma_i32_16x16x64_i8 v[106:109], v[162:165], v[194:197], v[106:109]
	v_mfma_i32_16x16x64_i8 v[94:97], v[154:157], v[202:205], v[94:97]
	v_mfma_i32_16x16x64_i8 v[90:93], v[162:165], v[202:205], v[90:93]
	v_mfma_i32_16x16x64_i8 v[78:81], v[154:157], v[210:213], v[78:81]
	v_mfma_i32_16x16x64_i8 v[74:77], v[162:165], v[210:213], v[74:77]
	s_setprio 0
	s_setprio 1
	v_mfma_i32_16x16x64_i8 v[118:121], v[166:169], v[182:185], v[118:121]
	v_mfma_i32_16x16x64_i8 v[114:117], v[174:177], v[182:185], v[114:117]
	v_mfma_i32_16x16x64_i8 v[102:105], v[166:169], v[190:193], v[102:105]
	v_mfma_i32_16x16x64_i8 v[98:101], v[174:177], v[190:193], v[98:101]
	v_mfma_i32_16x16x64_i8 v[86:89], v[166:169], v[198:201], v[86:89]
	v_mfma_i32_16x16x64_i8 v[82:85], v[174:177], v[198:201], v[82:85]
	v_mfma_i32_16x16x64_i8 v[70:73], v[166:169], v[206:209], v[70:73]
	v_mfma_i32_16x16x64_i8 v[66:69], v[174:177], v[206:209], v[66:69]
	v_mfma_i32_16x16x64_i8 v[118:121], v[170:173], v[186:189], v[118:121]
	v_mfma_i32_16x16x64_i8 v[114:117], v[178:181], v[186:189], v[114:117]
	v_mfma_i32_16x16x64_i8 v[102:105], v[170:173], v[194:197], v[102:105]
	v_mfma_i32_16x16x64_i8 v[98:101], v[178:181], v[194:197], v[98:101]
	v_mfma_i32_16x16x64_i8 v[86:89], v[170:173], v[202:205], v[86:89]
	v_mfma_i32_16x16x64_i8 v[82:85], v[178:181], v[202:205], v[82:85]
	v_mfma_i32_16x16x64_i8 v[70:73], v[170:173], v[210:213], v[70:73]
	v_mfma_i32_16x16x64_i8 v[66:69], v[178:181], v[210:213], v[66:69]
	s_setprio 0
	s_barrier
	v_mov_b32_e32 v0, v143
	ds_read_b128 v[182:185], v148 offset:49152
	ds_read_b128 v[186:189], v148 offset:50176
	ds_read_b128 v[190:193], v148 offset:51200
	ds_read_b128 v[194:197], v148 offset:52224
	ds_read_b128 v[198:201], v148 offset:53248
	ds_read_b128 v[202:205], v148 offset:54272
	ds_read_b128 v[206:209], v148 offset:55296
	ds_read_b128 v[210:213], v148 offset:56320
	s_add_i32 s84, s86, s40
	v_lshl_add_u64 v[130:131], s[50:51], 0, v[0:1]
	v_lshl_add_u64 v[130:131], v[130:131], 0, s[38:39]
	s_mov_b32 m0, s84
	v_mov_b32_e32 v0, v144
	global_load_lds_dwordx4 v[130:131], off
	s_add_i32 m0, s84, 0x2000
	s_nop 0
	v_lshl_add_u64 v[130:131], s[50:51], 0, v[0:1]
	s_add_u32 s50, s50, 0x20080
	v_lshl_add_u64 v[130:131], v[130:131], 0, s[38:39]
	s_addc_u32 s51, s51, 0
	v_mov_b32_e32 v0, v143
	s_add_i32 s84, s87, s40
	global_load_lds_dwordx4 v[130:131], off
	s_mov_b32 m0, s84
	s_nop 0
	global_load_lds_dwordx4 v0, s[50:51]
	v_mov_b32_e32 v0, v144
	s_add_i32 m0, s84, 0x2000
	s_nop 0
	global_load_lds_dwordx4 v0, s[50:51]
	v_mov_b32_e32 v0, v132
	s_mov_b32 m0, s75
	v_lshl_add_u64 v[130:131], s[46:47], 0, v[0:1]
	v_lshl_add_u64 v[130:131], v[130:131], 0, s[38:39]
	v_mov_b32_e32 v0, v133
	global_load_lds_dwordx4 v[130:131], off
	s_mov_b32 m0, s78
	v_lshl_add_u64 v[130:131], s[46:47], 0, v[0:1]
	v_lshl_add_u64 v[130:131], v[130:131], 0, s[38:39]
	global_load_lds_dwordx4 v[130:131], off
	s_waitcnt vmcnt(8)
	s_waitcnt lgkmcnt(0)
	s_barrier
	s_setprio 1
	s_waitcnt lgkmcnt(0)
	v_mfma_i32_16x16x64_i8 v[62:65], v[150:153], v[182:185], v[62:65]
	v_mfma_i32_16x16x64_i8 v[58:61], v[158:161], v[182:185], v[58:61]
	v_mfma_i32_16x16x64_i8 v[46:49], v[150:153], v[190:193], v[46:49]
	v_mfma_i32_16x16x64_i8 v[42:45], v[158:161], v[190:193], v[42:45]
	v_mfma_i32_16x16x64_i8 v[30:33], v[150:153], v[198:201], v[30:33]
	v_mfma_i32_16x16x64_i8 v[26:29], v[158:161], v[198:201], v[26:29]
	v_mfma_i32_16x16x64_i8 v[14:17], v[150:153], v[206:209], v[14:17]
	v_mfma_i32_16x16x64_i8 v[10:13], v[158:161], v[206:209], v[10:13]
	v_mfma_i32_16x16x64_i8 v[62:65], v[154:157], v[186:189], v[62:65]
	v_mfma_i32_16x16x64_i8 v[58:61], v[162:165], v[186:189], v[58:61]
	v_mfma_i32_16x16x64_i8 v[46:49], v[154:157], v[194:197], v[46:49]
	v_mfma_i32_16x16x64_i8 v[42:45], v[162:165], v[194:197], v[42:45]
	v_mfma_i32_16x16x64_i8 v[30:33], v[154:157], v[202:205], v[30:33]
	v_mfma_i32_16x16x64_i8 v[26:29], v[162:165], v[202:205], v[26:29]
	v_mfma_i32_16x16x64_i8 v[14:17], v[154:157], v[210:213], v[14:17]
	v_mfma_i32_16x16x64_i8 v[10:13], v[162:165], v[210:213], v[10:13]
	s_setprio 0
	s_setprio 1
	v_mfma_i32_16x16x64_i8 v[54:57], v[166:169], v[182:185], v[54:57]
	v_mfma_i32_16x16x64_i8 v[50:53], v[174:177], v[182:185], v[50:53]
	v_mfma_i32_16x16x64_i8 v[38:41], v[166:169], v[190:193], v[38:41]
	v_mfma_i32_16x16x64_i8 v[34:37], v[174:177], v[190:193], v[34:37]
	v_mfma_i32_16x16x64_i8 v[22:25], v[166:169], v[198:201], v[22:25]
	v_mfma_i32_16x16x64_i8 v[18:21], v[174:177], v[198:201], v[18:21]
	v_mfma_i32_16x16x64_i8 v[6:9], v[166:169], v[206:209], v[6:9]
	v_mfma_i32_16x16x64_i8 v[2:5], v[174:177], v[206:209], v[2:5]
	v_mfma_i32_16x16x64_i8 v[54:57], v[170:173], v[186:189], v[54:57]
	v_mfma_i32_16x16x64_i8 v[50:53], v[178:181], v[186:189], v[50:53]
	v_mfma_i32_16x16x64_i8 v[38:41], v[170:173], v[194:197], v[38:41]
	v_mfma_i32_16x16x64_i8 v[34:37], v[178:181], v[194:197], v[34:37]
	v_mfma_i32_16x16x64_i8 v[22:25], v[170:173], v[202:205], v[22:25]
	v_mfma_i32_16x16x64_i8 v[18:21], v[178:181], v[202:205], v[18:21]
	v_mfma_i32_16x16x64_i8 v[6:9], v[170:173], v[210:213], v[6:9]
	v_mfma_i32_16x16x64_i8 v[2:5], v[178:181], v[210:213], v[2:5]
	s_setprio 0
	s_barrier
	s_add_i32 s65, s65, 2
	s_add_u32 s48, s48, 0x100
	s_addc_u32 s49, s49, 0
	s_add_u32 s25, s25, 0x100
	s_addc_u32 s64, s64, 0
	s_cmp_gt_u32 s65, 5
	s_cbranch_scc0 .LBB0_445
	s_branch .Lpeel_exit_445

.Lpeel_exit_445:
.LBB0_448:
	v_mov_b32_e32 v0, v145
	v_mov_b32_e32 v130, v134
	s_lshl_b32 s25, s24, 7
	s_or_b32 s25, s25, s74
	s_mul_i32 s46, s71, 0x180000
	v_add_u32_e32 v149, s41, v130
	v_lshl_add_u32 v130, v0, 3, s25
	s_mul_hi_i32 s25, s71, 0x180000
	s_add_u32 s46, s67, s46
	s_addc_u32 s47, s68, s25
	s_lshl_b32 s24, s24, 3
	s_or_b32 s24, s24, s70
	s_ashr_i32 s25, s24, 31
	s_lshl_b64 s[24:25], s[24:25], 2
	s_add_u32 s24, s26, s24
	s_addc_u32 s25, s69, s25
	global_load_dword v150, v1, s[24:25]
	global_load_dword v151, v1, s[24:25] offset:16
	v_cvt_f32_i32_e32 v127, v127
	v_cvt_f32_i32_e32 v126, v126
	v_cvt_f32_i32_e32 v129, v129
	v_cvt_f32_i32_e32 v128, v128
	v_cvt_f32_i32_e32 v123, v123
	v_cvt_f32_i32_e32 v122, v122
	v_cvt_f32_i32_e32 v125, v125
	v_cvt_f32_i32_e32 v124, v124
	v_cvt_f32_i32_e32 v119, v119
	v_cvt_f32_i32_e32 v118, v118
	v_cvt_f32_i32_e32 v121, v121
	v_cvt_f32_i32_e32 v120, v120
	v_cvt_f32_i32_e32 v117, v117
	v_cvt_f32_i32_e32 v116, v116
	v_cvt_f32_i32_e32 v115, v115
	v_cvt_f32_i32_e32 v114, v114
	v_ashrrev_i32_e32 v131, 31, v130
	v_lshl_add_u64 v[130:131], v[130:131], 1, s[46:47]
	v_cvt_f32_i32_e32 v105, v105
	v_cvt_f32_i32_e32 v104, v104
	v_cvt_f32_i32_e32 v103, v103
	v_cvt_f32_i32_e32 v102, v102
	v_cvt_f32_i32_e32 v101, v101
	v_cvt_f32_i32_e32 v100, v100
	v_cvt_f32_i32_e32 v99, v99
	v_cvt_f32_i32_e32 v98, v98
	v_cvt_f32_i32_e32 v107, v107
	v_cvt_f32_i32_e32 v106, v106
	v_cvt_f32_i32_e32 v109, v109
	v_cvt_f32_i32_e32 v108, v108
	v_cvt_f32_i32_e32 v95, v95
	v_cvt_f32_i32_e32 v94, v94
	v_cvt_f32_i32_e32 v97, v97
	v_cvt_f32_i32_e32 v96, v96
	v_cvt_f32_i32_e32 v91, v91
	v_cvt_f32_i32_e32 v90, v90
	v_cvt_f32_i32_e32 v93, v93
	v_cvt_f32_i32_e32 v92, v92
	v_cvt_f32_i32_e32 v87, v87
	v_cvt_f32_i32_e32 v86, v86
	v_cvt_f32_i32_e32 v89, v89
	v_cvt_f32_i32_e32 v88, v88
	v_cvt_f32_i32_e32 v79, v79
	v_cvt_f32_i32_e32 v78, v78
	v_cvt_f32_i32_e32 v81, v81
	v_cvt_f32_i32_e32 v80, v80
	v_cvt_f32_i32_e32 v75, v75
	v_cvt_f32_i32_e32 v74, v74
	v_cvt_f32_i32_e32 v77, v77
	v_cvt_f32_i32_e32 v76, v76
	v_cvt_f32_i32_e32 v85, v85
	v_cvt_f32_i32_e32 v84, v84
	v_cvt_f32_i32_e32 v83, v83
	v_cvt_f32_i32_e32 v82, v82
	v_cvt_f32_i32_e32 v71, v71
	v_cvt_f32_i32_e32 v70, v70
	v_cvt_f32_i32_e32 v73, v73
	v_cvt_f32_i32_e32 v72, v72
	v_cvt_f32_i32_e32 v63, v63
	v_cvt_f32_i32_e32 v62, v62
	v_cvt_f32_i32_e32 v65, v65
	v_cvt_f32_i32_e32 v64, v64
	v_cvt_f32_i32_e32 v59, v59
	v_cvt_f32_i32_e32 v58, v58
	v_cvt_f32_i32_e32 v61, v61
	v_cvt_f32_i32_e32 v60, v60
	v_cvt_f32_i32_e32 v69, v69
	v_cvt_f32_i32_e32 v68, v68
	v_cvt_f32_i32_e32 v67, v67
	v_cvt_f32_i32_e32 v66, v66
	v_cvt_f32_i32_e32 v55, v55
	v_cvt_f32_i32_e32 v54, v54
	v_cvt_f32_i32_e32 v57, v57
	v_cvt_f32_i32_e32 v56, v56
	v_cvt_f32_i32_e32 v47, v47
	v_cvt_f32_i32_e32 v46, v46
	v_cvt_f32_i32_e32 v49, v49
	v_cvt_f32_i32_e32 v48, v48
	s_and_b64 vcc, exec, s[10:11]
	s_cbranch_vccz .Lepi_lead_448
	s_barrier
.Lepi_lead_448:
	s_waitcnt vmcnt(0)
	v_mul_f32_e32 v0, v135, v150
	v_pk_mul_f32 v[126:127], v[0:1], v[126:127] op_sel_hi:[0,1]
	v_pk_mul_f32 v[128:129], v[0:1], v[128:129] op_sel_hi:[0,1]
	v_pk_mul_f32 v[124:125], v[0:1], v[124:125] op_sel_hi:[0,1]
	v_pk_mul_f32 v[122:123], v[0:1], v[122:123] op_sel_hi:[0,1]
	v_mul_f32_e32 v0, 0xbfb8aa3b, v126
	v_exp_f32_e32 v0, v0
	v_mul_f32_e32 v152, v135, v151
	v_pk_mul_f32 v[118:119], v[152:153], v[118:119] op_sel_hi:[0,1]
	v_pk_mul_f32 v[120:121], v[152:153], v[120:121] op_sel_hi:[0,1]
	v_add_f32_e32 v0, 1.0, v0
	v_rcp_f32_e32 v154, v0
	v_mul_f32_e32 v0, 0xbfb8aa3b, v127
	v_exp_f32_e32 v0, v0
	v_pk_mul_f32 v[114:115], v[152:153], v[114:115] op_sel_hi:[0,1]
	v_pk_mul_f32 v[116:117], v[152:153], v[116:117] op_sel_hi:[0,1]
	v_mad_i64_i32 v[152:153], s[24:25], v149, s52, v[130:131]
	v_add_f32_e32 v0, 1.0, v0
	v_rcp_f32_e32 v155, v0
	v_mul_f32_e32 v0, 0xbfb8aa3b, v128
	v_exp_f32_e32 v0, v0
	v_cvt_f32_i32_e32 v43, v43
	v_pk_mul_f32 v[126:127], v[126:127], v[154:155]
	v_cvt_f32_i32_e32 v42, v42
	v_add_f32_e32 v0, 1.0, v0
	v_rcp_f32_e32 v156, v0
	v_mul_f32_e32 v0, 0xbfb8aa3b, v129
	v_exp_f32_e32 v0, v0
	v_pk_mul_f32 v[118:119], v[118:119], v[126:127]
	v_cvt_f32_i32_e32 v45, v45
	v_cvt_f32_i32_e32 v44, v44
	v_add_f32_e32 v0, 1.0, v0
	v_rcp_f32_e32 v157, v0
	v_mul_f32_e32 v0, 0xbfb8aa3b, v122
	v_exp_f32_e32 v0, v0
	v_cvt_f32_i32_e32 v53, v53
	v_pk_mul_f32 v[128:129], v[128:129], v[156:157]
	v_cvt_f32_i32_e32 v52, v52
	v_add_f32_e32 v0, 1.0, v0
	v_rcp_f32_e32 v126, v0
	v_mul_f32_e32 v0, 0xbfb8aa3b, v123
	v_exp_f32_e32 v0, v0
	v_pk_mul_f32 v[120:121], v[120:121], v[128:129]
	v_cvt_f32_i32_e32 v51, v51
	v_cvt_f32_i32_e32 v50, v50
	v_add_f32_e32 v0, 1.0, v0
	v_rcp_f32_e32 v127, v0
	v_mul_f32_e32 v0, 0xbfb8aa3b, v124
	v_exp_f32_e32 v0, v0
	v_cvt_f32_i32_e32 v39, v39
	v_pk_mul_f32 v[122:123], v[122:123], v[126:127]
	v_cvt_f32_i32_e32 v38, v38
	v_add_f32_e32 v0, 1.0, v0
	v_rcp_f32_e32 v128, v0
	v_mul_f32_e32 v0, 0xbfb8aa3b, v125
	v_exp_f32_e32 v0, v0
	v_cvt_f32_i32_e32 v41, v41
	v_cvt_f32_i32_e32 v40, v40
	v_cvt_f32_i32_e32 v31, v31
	v_add_f32_e32 v0, 1.0, v0
	v_rcp_f32_e32 v129, v0
	v_mul_f32_e32 v0, v136, v151
	v_pk_mul_f32 v[102:103], v[0:1], v[102:103] op_sel_hi:[0,1]
	v_pk_mul_f32 v[104:105], v[0:1], v[104:105] op_sel_hi:[0,1]
	v_pk_mul_f32 v[124:125], v[124:125], v[128:129]
	v_pk_mul_f32 v[98:99], v[0:1], v[98:99] op_sel_hi:[0,1]
	v_pk_mul_f32 v[124:125], v[116:117], v[124:125]
	v_pk_mul_f32 v[116:117], v[114:115], v[122:123]
	v_cvt_pk_bf16_f32 v114, v118, v119
	v_cvt_pk_bf16_f32 v115, v120, v121
	v_pk_mul_f32 v[100:101], v[0:1], v[100:101] op_sel_hi:[0,1]
	v_cvt_pk_bf16_f32 v116, v116, v117
	v_cvt_pk_bf16_f32 v117, v124, v125
	global_store_dwordx4 v[152:153], v[114:117], off
	v_cvt_f32_i32_e32 v30, v30
	v_cvt_f32_i32_e32 v33, v33
	v_cvt_f32_i32_e32 v117, v111
	v_cvt_f32_i32_e32 v116, v110
	v_add_u32_e32 v115, 16, v149
	v_mul_f32_e32 v114, v136, v150
	v_cvt_f32_i32_e32 v111, v113
	v_cvt_f32_i32_e32 v110, v112
	v_pk_mul_f32 v[112:113], v[114:115], v[116:117] op_sel_hi:[0,1]
	v_mul_f32_e32 v0, 0xbfb8aa3b, v112
	v_exp_f32_e32 v0, v0
	v_pk_mul_f32 v[110:111], v[114:115], v[110:111] op_sel_hi:[0,1]
	v_pk_mul_f32 v[106:107], v[114:115], v[106:107] op_sel_hi:[0,1]
	v_pk_mul_f32 v[108:109], v[114:115], v[108:109] op_sel_hi:[0,1]
	v_add_f32_e32 v0, 1.0, v0
	v_rcp_f32_e32 v116, v0
	v_mul_f32_e32 v0, 0xbfb8aa3b, v113
	v_exp_f32_e32 v0, v0
	v_mad_i64_i32 v[114:115], s[24:25], v115, s52, v[130:131]
	v_cvt_f32_i32_e32 v32, v32
	v_add_f32_e32 v0, 1.0, v0
	v_rcp_f32_e32 v117, v0
	v_mul_f32_e32 v0, 0xbfb8aa3b, v110
	v_exp_f32_e32 v0, v0
	v_cvt_f32_i32_e32 v27, v27
	v_pk_mul_f32 v[112:113], v[112:113], v[116:117]
	v_cvt_f32_i32_e32 v26, v26
	v_add_f32_e32 v0, 1.0, v0
	v_rcp_f32_e32 v118, v0
	v_mul_f32_e32 v0, 0xbfb8aa3b, v111
	v_exp_f32_e32 v0, v0
	v_pk_mul_f32 v[102:103], v[102:103], v[112:113]
	v_cvt_f32_i32_e32 v29, v29
	v_cvt_f32_i32_e32 v28, v28
	v_add_f32_e32 v0, 1.0, v0
	v_rcp_f32_e32 v119, v0
	v_mul_f32_e32 v0, 0xbfb8aa3b, v106
	v_exp_f32_e32 v0, v0
	v_cvt_f32_i32_e32 v37, v37
	v_pk_mul_f32 v[110:111], v[110:111], v[118:119]
	v_cvt_f32_i32_e32 v36, v36
	v_add_f32_e32 v0, 1.0, v0
	v_pk_mul_f32 v[104:105], v[104:105], v[110:111]
	v_rcp_f32_e32 v110, v0
	v_mul_f32_e32 v0, 0xbfb8aa3b, v107
	v_exp_f32_e32 v0, v0
	v_cvt_f32_i32_e32 v35, v35
	v_cvt_f32_i32_e32 v34, v34
	v_cvt_f32_i32_e32 v23, v23
	v_add_f32_e32 v0, 1.0, v0
	v_rcp_f32_e32 v111, v0
	v_mul_f32_e32 v0, 0xbfb8aa3b, v108
	v_exp_f32_e32 v0, v0
	v_cvt_f32_i32_e32 v22, v22
	v_pk_mul_f32 v[106:107], v[106:107], v[110:111]
	v_cvt_f32_i32_e32 v25, v25
	v_add_f32_e32 v0, 1.0, v0
	v_rcp_f32_e32 v112, v0
	v_mul_f32_e32 v0, 0xbfb8aa3b, v109
	v_exp_f32_e32 v0, v0
	v_cvt_f32_i32_e32 v24, v24
	v_cvt_f32_i32_e32 v15, v15
	v_cvt_f32_i32_e32 v14, v14
	v_add_f32_e32 v0, 1.0, v0
	v_rcp_f32_e32 v113, v0
	v_mul_f32_e32 v0, v137, v150
	v_pk_mul_f32 v[94:95], v[0:1], v[94:95] op_sel_hi:[0,1]
	v_pk_mul_f32 v[96:97], v[0:1], v[96:97] op_sel_hi:[0,1]
	v_pk_mul_f32 v[92:93], v[0:1], v[92:93] op_sel_hi:[0,1]
	v_pk_mul_f32 v[90:91], v[0:1], v[90:91] op_sel_hi:[0,1]
	v_mul_f32_e32 v0, 0xbfb8aa3b, v94
	v_exp_f32_e32 v0, v0
	v_pk_mul_f32 v[108:109], v[108:109], v[112:113]
	v_cvt_f32_i32_e32 v17, v17
	v_pk_mul_f32 v[108:109], v[100:101], v[108:109]
	v_pk_mul_f32 v[100:101], v[98:99], v[106:107]
	v_cvt_pk_bf16_f32 v98, v102, v103
	v_cvt_pk_bf16_f32 v99, v104, v105
	v_add_f32_e32 v0, 1.0, v0
	v_cvt_pk_bf16_f32 v100, v100, v101
	v_cvt_pk_bf16_f32 v101, v108, v109
	global_store_dwordx4 v[114:115], v[98:101], off
	v_cvt_f32_i32_e32 v16, v16
	v_cvt_f32_i32_e32 v11, v11
	v_rcp_f32_e32 v100, v0
	v_mul_f32_e32 v0, 0xbfb8aa3b, v95
	v_exp_f32_e32 v0, v0
	v_add_u32_e32 v99, 32, v149
	v_mul_f32_e32 v98, v137, v151
	v_pk_mul_f32 v[86:87], v[98:99], v[86:87] op_sel_hi:[0,1]
	v_add_f32_e32 v0, 1.0, v0
	v_rcp_f32_e32 v101, v0
	v_mul_f32_e32 v0, 0xbfb8aa3b, v96
	v_exp_f32_e32 v0, v0
	v_pk_mul_f32 v[88:89], v[98:99], v[88:89] op_sel_hi:[0,1]
	v_pk_mul_f32 v[94:95], v[94:95], v[100:101]
	v_pk_mul_f32 v[82:83], v[98:99], v[82:83] op_sel_hi:[0,1]
	v_add_f32_e32 v0, 1.0, v0
	v_rcp_f32_e32 v102, v0
	v_mul_f32_e32 v0, 0xbfb8aa3b, v97
	v_exp_f32_e32 v0, v0
	v_pk_mul_f32 v[86:87], v[86:87], v[94:95]
	v_pk_mul_f32 v[84:85], v[98:99], v[84:85] op_sel_hi:[0,1]
	v_mad_i64_i32 v[98:99], s[24:25], v99, s52, v[130:131]
	v_add_f32_e32 v0, 1.0, v0
	v_rcp_f32_e32 v103, v0
	v_mul_f32_e32 v0, 0xbfb8aa3b, v90
	v_exp_f32_e32 v0, v0
	v_cvt_f32_i32_e32 v10, v10
	v_pk_mul_f32 v[96:97], v[96:97], v[102:103]
	v_cvt_f32_i32_e32 v13, v13
	v_add_f32_e32 v0, 1.0, v0
	v_rcp_f32_e32 v94, v0
	v_mul_f32_e32 v0, 0xbfb8aa3b, v91
	v_exp_f32_e32 v0, v0
	v_pk_mul_f32 v[88:89], v[88:89], v[96:97]
	v_cvt_f32_i32_e32 v12, v12
	v_cvt_f32_i32_e32 v21, v21
	v_add_f32_e32 v0, 1.0, v0
	v_rcp_f32_e32 v95, v0
	v_mul_f32_e32 v0, 0xbfb8aa3b, v92
	v_exp_f32_e32 v0, v0
	v_cvt_f32_i32_e32 v20, v20
	v_pk_mul_f32 v[90:91], v[90:91], v[94:95]
	v_cvt_f32_i32_e32 v19, v19
	v_add_f32_e32 v0, 1.0, v0
	v_rcp_f32_e32 v96, v0
	v_mul_f32_e32 v0, 0xbfb8aa3b, v93
	v_exp_f32_e32 v0, v0
	v_cvt_f32_i32_e32 v18, v18
	v_cvt_f32_i32_e32 v7, v7
	v_cvt_f32_i32_e32 v6, v6
	v_add_f32_e32 v0, 1.0, v0
	v_rcp_f32_e32 v97, v0
	v_mul_f32_e32 v0, v138, v150
	v_pk_mul_f32 v[78:79], v[0:1], v[78:79] op_sel_hi:[0,1]
	v_pk_mul_f32 v[80:81], v[0:1], v[80:81] op_sel_hi:[0,1]
	v_pk_mul_f32 v[76:77], v[0:1], v[76:77] op_sel_hi:[0,1]
	v_pk_mul_f32 v[74:75], v[0:1], v[74:75] op_sel_hi:[0,1]
	v_mul_f32_e32 v0, 0xbfb8aa3b, v78
	v_exp_f32_e32 v0, v0
	v_pk_mul_f32 v[92:93], v[92:93], v[96:97]
	v_cvt_f32_i32_e32 v9, v9
	v_pk_mul_f32 v[92:93], v[84:85], v[92:93]
	v_pk_mul_f32 v[84:85], v[82:83], v[90:91]
	v_cvt_pk_bf16_f32 v82, v86, v87
	v_cvt_pk_bf16_f32 v83, v88, v89
	v_add_f32_e32 v0, 1.0, v0
	v_cvt_pk_bf16_f32 v84, v84, v85
	v_cvt_pk_bf16_f32 v85, v92, v93
	global_store_dwordx4 v[98:99], v[82:85], off
	v_cvt_f32_i32_e32 v8, v8
	v_cvt_f32_i32_e32 v5, v5
	v_rcp_f32_e32 v84, v0
	v_mul_f32_e32 v0, 0xbfb8aa3b, v79
	v_exp_f32_e32 v0, v0
	v_add_u32_e32 v83, 48, v149
	v_mul_f32_e32 v82, v138, v151
	v_pk_mul_f32 v[70:71], v[82:83], v[70:71] op_sel_hi:[0,1]
	v_add_f32_e32 v0, 1.0, v0
	v_rcp_f32_e32 v85, v0
	v_mul_f32_e32 v0, 0xbfb8aa3b, v80
	v_exp_f32_e32 v0, v0
	v_pk_mul_f32 v[72:73], v[82:83], v[72:73] op_sel_hi:[0,1]
	v_pk_mul_f32 v[78:79], v[78:79], v[84:85]
	v_pk_mul_f32 v[66:67], v[82:83], v[66:67] op_sel_hi:[0,1]
	v_add_f32_e32 v0, 1.0, v0
	v_rcp_f32_e32 v86, v0
	v_mul_f32_e32 v0, 0xbfb8aa3b, v81
	v_exp_f32_e32 v0, v0
	v_pk_mul_f32 v[70:71], v[70:71], v[78:79]
	v_pk_mul_f32 v[68:69], v[82:83], v[68:69] op_sel_hi:[0,1]
	v_mad_i64_i32 v[82:83], s[24:25], v83, s52, v[130:131]
	v_add_f32_e32 v0, 1.0, v0
	v_rcp_f32_e32 v87, v0
	v_mul_f32_e32 v0, 0xbfb8aa3b, v74
	v_exp_f32_e32 v0, v0
	v_cvt_f32_i32_e32 v4, v4
	v_pk_mul_f32 v[80:81], v[80:81], v[86:87]
	v_cvt_f32_i32_e32 v3, v3
	v_add_f32_e32 v0, 1.0, v0
	v_rcp_f32_e32 v78, v0
	v_mul_f32_e32 v0, 0xbfb8aa3b, v75
	v_exp_f32_e32 v0, v0
	v_pk_mul_f32 v[72:73], v[72:73], v[80:81]
	v_cvt_f32_i32_e32 v2, v2
	s_andn2_b64 vcc, exec, s[22:23]
	v_add_f32_e32 v0, 1.0, v0
	v_rcp_f32_e32 v79, v0
	v_mul_f32_e32 v0, 0xbfb8aa3b, v76
	v_exp_f32_e32 v0, v0
	v_pk_mul_f32 v[74:75], v[74:75], v[78:79]
	v_add_f32_e32 v0, 1.0, v0
	v_rcp_f32_e32 v80, v0
	v_mul_f32_e32 v0, 0xbfb8aa3b, v77
	v_exp_f32_e32 v0, v0
	s_nop 0
	v_add_f32_e32 v0, 1.0, v0
	v_rcp_f32_e32 v81, v0
	v_mul_f32_e32 v0, v139, v150
	v_pk_mul_f32 v[62:63], v[0:1], v[62:63] op_sel_hi:[0,1]
	v_pk_mul_f32 v[64:65], v[0:1], v[64:65] op_sel_hi:[0,1]
	v_pk_mul_f32 v[60:61], v[0:1], v[60:61] op_sel_hi:[0,1]
	v_pk_mul_f32 v[58:59], v[0:1], v[58:59] op_sel_hi:[0,1]
	v_mul_f32_e32 v0, 0xbfb8aa3b, v62
	v_exp_f32_e32 v0, v0
	v_pk_mul_f32 v[76:77], v[76:77], v[80:81]
	v_add_f32_e32 v0, 1.0, v0
	v_pk_mul_f32 v[76:77], v[68:69], v[76:77]
	v_pk_mul_f32 v[68:69], v[66:67], v[74:75]
	v_cvt_pk_bf16_f32 v66, v70, v71
	v_cvt_pk_bf16_f32 v67, v72, v73
	s_nop 0
	v_cvt_pk_bf16_f32 v68, v68, v69
	v_cvt_pk_bf16_f32 v69, v76, v77
	global_store_dwordx4 v[82:83], v[66:69], off
	s_nop 1
	v_rcp_f32_e32 v68, v0
	v_mul_f32_e32 v0, 0xbfb8aa3b, v63
	v_exp_f32_e32 v0, v0
	v_add_u32_e32 v67, 0x80, v149
	v_mul_f32_e32 v66, v139, v151
	v_pk_mul_f32 v[54:55], v[66:67], v[54:55] op_sel_hi:[0,1]
	v_add_f32_e32 v0, 1.0, v0
	v_rcp_f32_e32 v69, v0
	v_mul_f32_e32 v0, 0xbfb8aa3b, v64
	v_exp_f32_e32 v0, v0
	v_pk_mul_f32 v[56:57], v[66:67], v[56:57] op_sel_hi:[0,1]
	v_pk_mul_f32 v[62:63], v[62:63], v[68:69]
	v_pk_mul_f32 v[50:51], v[66:67], v[50:51] op_sel_hi:[0,1]
	v_add_f32_e32 v0, 1.0, v0
	v_rcp_f32_e32 v70, v0
	v_mul_f32_e32 v0, 0xbfb8aa3b, v65
	v_exp_f32_e32 v0, v0
	v_pk_mul_f32 v[54:55], v[54:55], v[62:63]
	v_pk_mul_f32 v[52:53], v[66:67], v[52:53] op_sel_hi:[0,1]
	v_mad_i64_i32 v[66:67], s[24:25], v67, s52, v[130:131]
	v_add_f32_e32 v0, 1.0, v0
	v_rcp_f32_e32 v71, v0
	v_mul_f32_e32 v0, 0xbfb8aa3b, v58
	v_exp_f32_e32 v0, v0
	v_pk_mul_f32 v[64:65], v[64:65], v[70:71]
	s_nop 0
	v_pk_mul_f32 v[56:57], v[56:57], v[64:65]
	v_add_f32_e32 v0, 1.0, v0
	v_rcp_f32_e32 v62, v0
	v_mul_f32_e32 v0, 0xbfb8aa3b, v59
	v_exp_f32_e32 v0, v0
	s_nop 0
	v_add_f32_e32 v0, 1.0, v0
	v_rcp_f32_e32 v63, v0
	v_mul_f32_e32 v0, 0xbfb8aa3b, v60
	v_exp_f32_e32 v0, v0
	v_pk_mul_f32 v[58:59], v[58:59], v[62:63]
	v_add_f32_e32 v0, 1.0, v0
	v_rcp_f32_e32 v64, v0
	v_mul_f32_e32 v0, 0xbfb8aa3b, v61
	v_exp_f32_e32 v0, v0
	s_nop 0
	v_add_f32_e32 v0, 1.0, v0
	v_rcp_f32_e32 v65, v0
	v_mul_f32_e32 v0, v140, v150
	v_pk_mul_f32 v[46:47], v[0:1], v[46:47] op_sel_hi:[0,1]
	v_pk_mul_f32 v[48:49], v[0:1], v[48:49] op_sel_hi:[0,1]
	v_pk_mul_f32 v[44:45], v[0:1], v[44:45] op_sel_hi:[0,1]
	v_pk_mul_f32 v[42:43], v[0:1], v[42:43] op_sel_hi:[0,1]
	v_mul_f32_e32 v0, 0xbfb8aa3b, v46
	v_exp_f32_e32 v0, v0
	v_pk_mul_f32 v[60:61], v[60:61], v[64:65]
	v_add_f32_e32 v0, 1.0, v0
	v_pk_mul_f32 v[60:61], v[52:53], v[60:61]
	v_pk_mul_f32 v[52:53], v[50:51], v[58:59]
	v_cvt_pk_bf16_f32 v50, v54, v55
	v_cvt_pk_bf16_f32 v51, v56, v57
	s_nop 0
	v_cvt_pk_bf16_f32 v52, v52, v53
	v_cvt_pk_bf16_f32 v53, v60, v61
	global_store_dwordx4 v[66:67], v[50:53], off
	s_nop 1
	v_rcp_f32_e32 v52, v0
	v_mul_f32_e32 v0, 0xbfb8aa3b, v47
	v_exp_f32_e32 v0, v0
	v_add_u32_e32 v51, 0x90, v149
	v_mul_f32_e32 v50, v140, v151
	v_pk_mul_f32 v[38:39], v[50:51], v[38:39] op_sel_hi:[0,1]
	v_add_f32_e32 v0, 1.0, v0
	v_rcp_f32_e32 v53, v0
	v_mul_f32_e32 v0, 0xbfb8aa3b, v48
	v_exp_f32_e32 v0, v0
	v_pk_mul_f32 v[40:41], v[50:51], v[40:41] op_sel_hi:[0,1]
	v_pk_mul_f32 v[46:47], v[46:47], v[52:53]
	v_pk_mul_f32 v[34:35], v[50:51], v[34:35] op_sel_hi:[0,1]
	v_add_f32_e32 v0, 1.0, v0
	v_rcp_f32_e32 v54, v0
	v_mul_f32_e32 v0, 0xbfb8aa3b, v49
	v_exp_f32_e32 v0, v0
	v_pk_mul_f32 v[38:39], v[38:39], v[46:47]
	v_pk_mul_f32 v[36:37], v[50:51], v[36:37] op_sel_hi:[0,1]
	v_mad_i64_i32 v[50:51], s[24:25], v51, s52, v[130:131]
	v_add_f32_e32 v0, 1.0, v0
	v_rcp_f32_e32 v55, v0
	v_mul_f32_e32 v0, 0xbfb8aa3b, v42
	v_exp_f32_e32 v0, v0
	v_pk_mul_f32 v[48:49], v[48:49], v[54:55]
	s_nop 0
	v_pk_mul_f32 v[40:41], v[40:41], v[48:49]
	v_add_f32_e32 v0, 1.0, v0
	v_rcp_f32_e32 v46, v0
	v_mul_f32_e32 v0, 0xbfb8aa3b, v43
	v_exp_f32_e32 v0, v0
	s_nop 0
	v_add_f32_e32 v0, 1.0, v0
	v_rcp_f32_e32 v47, v0
	v_mul_f32_e32 v0, 0xbfb8aa3b, v44
	v_exp_f32_e32 v0, v0
	v_pk_mul_f32 v[42:43], v[42:43], v[46:47]
	v_add_f32_e32 v0, 1.0, v0
	v_rcp_f32_e32 v48, v0
	v_mul_f32_e32 v0, 0xbfb8aa3b, v45
	v_exp_f32_e32 v0, v0
	s_nop 0
	v_add_f32_e32 v0, 1.0, v0
	v_rcp_f32_e32 v49, v0
	v_mul_f32_e32 v0, v141, v150
	v_pk_mul_f32 v[30:31], v[0:1], v[30:31] op_sel_hi:[0,1]
	v_pk_mul_f32 v[32:33], v[0:1], v[32:33] op_sel_hi:[0,1]
	v_pk_mul_f32 v[28:29], v[0:1], v[28:29] op_sel_hi:[0,1]
	v_pk_mul_f32 v[26:27], v[0:1], v[26:27] op_sel_hi:[0,1]
	v_mul_f32_e32 v0, 0xbfb8aa3b, v30
	v_exp_f32_e32 v0, v0
	v_pk_mul_f32 v[44:45], v[44:45], v[48:49]
	v_add_f32_e32 v0, 1.0, v0
	v_pk_mul_f32 v[44:45], v[36:37], v[44:45]
	v_pk_mul_f32 v[36:37], v[34:35], v[42:43]
	v_cvt_pk_bf16_f32 v34, v38, v39
	v_cvt_pk_bf16_f32 v35, v40, v41
	s_nop 0
	v_cvt_pk_bf16_f32 v36, v36, v37
	v_cvt_pk_bf16_f32 v37, v44, v45
	global_store_dwordx4 v[50:51], v[34:37], off
	s_nop 1
	v_rcp_f32_e32 v36, v0
	v_mul_f32_e32 v0, 0xbfb8aa3b, v31
	v_exp_f32_e32 v0, v0
	v_add_u32_e32 v35, 0xa0, v149
	v_mul_f32_e32 v34, v141, v151
	v_pk_mul_f32 v[22:23], v[34:35], v[22:23] op_sel_hi:[0,1]
	v_add_f32_e32 v0, 1.0, v0
	v_rcp_f32_e32 v37, v0
	v_mul_f32_e32 v0, 0xbfb8aa3b, v32
	v_exp_f32_e32 v0, v0
	v_pk_mul_f32 v[24:25], v[34:35], v[24:25] op_sel_hi:[0,1]
	v_pk_mul_f32 v[30:31], v[30:31], v[36:37]
	v_pk_mul_f32 v[18:19], v[34:35], v[18:19] op_sel_hi:[0,1]
	v_add_f32_e32 v0, 1.0, v0
	v_rcp_f32_e32 v38, v0
	v_mul_f32_e32 v0, 0xbfb8aa3b, v33
	v_exp_f32_e32 v0, v0
	v_pk_mul_f32 v[22:23], v[22:23], v[30:31]
	v_pk_mul_f32 v[20:21], v[34:35], v[20:21] op_sel_hi:[0,1]
	v_mad_i64_i32 v[34:35], s[24:25], v35, s52, v[130:131]
	v_add_f32_e32 v0, 1.0, v0
	v_rcp_f32_e32 v39, v0
	v_mul_f32_e32 v0, 0xbfb8aa3b, v26
	v_exp_f32_e32 v0, v0
	v_pk_mul_f32 v[32:33], v[32:33], v[38:39]
	s_nop 0
	v_pk_mul_f32 v[24:25], v[24:25], v[32:33]
	v_add_f32_e32 v0, 1.0, v0
	v_rcp_f32_e32 v30, v0
	v_mul_f32_e32 v0, 0xbfb8aa3b, v27
	v_exp_f32_e32 v0, v0
	s_nop 0
	v_add_f32_e32 v0, 1.0, v0
	v_rcp_f32_e32 v31, v0
	v_mul_f32_e32 v0, 0xbfb8aa3b, v28
	v_exp_f32_e32 v0, v0
	v_pk_mul_f32 v[26:27], v[26:27], v[30:31]
	v_add_f32_e32 v0, 1.0, v0
	v_rcp_f32_e32 v32, v0
	v_mul_f32_e32 v0, 0xbfb8aa3b, v29
	v_exp_f32_e32 v0, v0
	s_nop 0
	v_add_f32_e32 v0, 1.0, v0
	v_rcp_f32_e32 v33, v0
	v_mul_f32_e32 v0, v142, v150
	v_pk_mul_f32 v[14:15], v[0:1], v[14:15] op_sel_hi:[0,1]
	v_pk_mul_f32 v[16:17], v[0:1], v[16:17] op_sel_hi:[0,1]
	v_pk_mul_f32 v[12:13], v[0:1], v[12:13] op_sel_hi:[0,1]
	v_pk_mul_f32 v[10:11], v[0:1], v[10:11] op_sel_hi:[0,1]
	v_mul_f32_e32 v0, 0xbfb8aa3b, v14
	v_exp_f32_e32 v0, v0
	v_pk_mul_f32 v[28:29], v[28:29], v[32:33]
	v_add_f32_e32 v0, 1.0, v0
	v_pk_mul_f32 v[28:29], v[20:21], v[28:29]
	v_pk_mul_f32 v[20:21], v[18:19], v[26:27]
	v_cvt_pk_bf16_f32 v18, v22, v23
	v_cvt_pk_bf16_f32 v19, v24, v25
	s_nop 0
	v_cvt_pk_bf16_f32 v20, v20, v21
	v_cvt_pk_bf16_f32 v21, v28, v29
	global_store_dwordx4 v[34:35], v[18:21], off
	s_nop 1
	v_rcp_f32_e32 v20, v0
	v_mul_f32_e32 v0, 0xbfb8aa3b, v15
	v_exp_f32_e32 v0, v0
	v_add_u32_e32 v19, 0xb0, v149
	v_mul_f32_e32 v18, v142, v151
	v_pk_mul_f32 v[6:7], v[18:19], v[6:7] op_sel_hi:[0,1]
	v_add_f32_e32 v0, 1.0, v0
	v_rcp_f32_e32 v21, v0
	v_mul_f32_e32 v0, 0xbfb8aa3b, v16
	v_exp_f32_e32 v0, v0
	v_pk_mul_f32 v[8:9], v[18:19], v[8:9] op_sel_hi:[0,1]
	v_pk_mul_f32 v[14:15], v[14:15], v[20:21]
	v_pk_mul_f32 v[2:3], v[18:19], v[2:3] op_sel_hi:[0,1]
	v_add_f32_e32 v0, 1.0, v0
	v_rcp_f32_e32 v22, v0
	v_mul_f32_e32 v0, 0xbfb8aa3b, v17
	v_exp_f32_e32 v0, v0
	v_pk_mul_f32 v[6:7], v[6:7], v[14:15]
	v_pk_mul_f32 v[4:5], v[18:19], v[4:5] op_sel_hi:[0,1]
	v_mad_i64_i32 v[18:19], s[24:25], v19, s52, v[130:131]
	v_add_f32_e32 v0, 1.0, v0
	v_rcp_f32_e32 v23, v0
	v_mul_f32_e32 v0, 0xbfb8aa3b, v10
	v_exp_f32_e32 v0, v0
	s_mov_b64 s[24:25], -1
	v_pk_mul_f32 v[16:17], v[16:17], v[22:23]
	v_add_f32_e32 v0, 1.0, v0
	v_rcp_f32_e32 v14, v0
	v_mul_f32_e32 v0, 0xbfb8aa3b, v11
	v_exp_f32_e32 v0, v0
	v_pk_mul_f32 v[8:9], v[8:9], v[16:17]
	v_add_f32_e32 v0, 1.0, v0
	v_rcp_f32_e32 v15, v0
	v_mul_f32_e32 v0, 0xbfb8aa3b, v12
	v_exp_f32_e32 v0, v0
	v_pk_mul_f32 v[10:11], v[10:11], v[14:15]
	v_add_f32_e32 v0, 1.0, v0
	v_rcp_f32_e32 v16, v0
	v_mul_f32_e32 v0, 0xbfb8aa3b, v13
	v_exp_f32_e32 v0, v0
	s_nop 0
	v_add_f32_e32 v0, 1.0, v0
	v_rcp_f32_e32 v17, v0
	s_nop 0
	v_pk_mul_f32 v[12:13], v[12:13], v[16:17]
	s_nop 0
	v_pk_mul_f32 v[12:13], v[4:5], v[12:13]
	v_pk_mul_f32 v[4:5], v[2:3], v[10:11]
	v_cvt_pk_bf16_f32 v2, v6, v7
	v_cvt_pk_bf16_f32 v3, v8, v9
	s_nop 0
	v_cvt_pk_bf16_f32 v4, v4, v5
	v_cvt_pk_bf16_f32 v5, v12, v13
	global_store_dwordx4 v[18:19], v[2:5], off
	s_cbranch_vccnz .LBB0_441
	s_cmp_eq_u32 s83, s71
	s_cbranch_scc1 .LBB0_451
	v_lshl_add_u32 v2, s83, 8, v146
	v_ashrrev_i32_e32 v3, 31, v2
	v_lshl_add_u64 v[2:3], v[2:3], 2, s[4:5]
	global_load_dword v135, v[2:3], off
	global_load_dword v136, v[2:3], off offset:64
	global_load_dword v137, v[2:3], off offset:128
	global_load_dword v138, v[2:3], off offset:192
	global_load_dword v139, v[2:3], off offset:512
	global_load_dword v140, v[2:3], off offset:576
	global_load_dword v141, v[2:3], off offset:640
	global_load_dword v142, v[2:3], off offset:704

.LBB0_645:
	s_or_b64 exec, exec, s[42:43]
	buffer_inv sc1
	s_waitcnt vmcnt(0)
	v_readfirstlane_b32 s2, v2
	s_nop 1
	v_add_u32_e32 v0, s2, v0
	v_and_b32_e32 v2, -4, v0
	v_and_b32_e32 v0, 3, v0
	v_cmp_eq_u32_e64 s[2:3], 3, v0
	v_add_u32_e32 v2, 4, v2
	s_and_b64 s[2:3], s[2:3], exec

.LBB0_738:
	s_or_b64 exec, exec, s[42:43]
	buffer_inv sc1
	s_waitcnt vmcnt(0)
	v_readfirstlane_b32 s2, v2
	s_nop 1
	v_add_u32_e32 v0, s2, v0
	v_and_b32_e32 v2, 0xffffffe0, v0
	v_and_b32_e32 v0, 31, v0
	v_cmp_eq_u32_e64 s[2:3], 31, v0
	v_add_u32_e32 v2, 32, v2
	s_and_b64 s[2:3], s[2:3], exec

.LBB0_843:
	s_or_b64 exec, exec, s[42:43]
	buffer_inv sc1
	s_waitcnt vmcnt(0)
	v_readfirstlane_b32 s4, v2
	s_nop 1
	v_add_u32_e32 v0, s4, v0
	v_and_b32_e32 v2, 3, v0
	v_cmp_ne_u32_e32 vcc, 3, v2
	s_and_saveexec_b64 s[40:41], vcc
	s_cbranch_execz .LBB0_858
	global_load_dword v2, v1, s[24:25] sc1
	v_bitop3_b32 v0, v0, -4, v0 bitop3:0xc
	s_waitcnt vmcnt(0)
	v_add_u32_e32 v2, v2, v0
	v_cmp_gt_i32_e32 vcc, 0, v2
	s_and_b64 exec, exec, vcc
	s_cbranch_execz .LBB0_858
	s_add_u32 s22, s22, 0x4200
	s_addc_u32 s23, s23, 0
	s_mov_b32 s4, 1
	s_mov_b64 s[42:43], 0
	s_branch .LBB0_847

.LBB0_891:
	s_or_b64 exec, exec, s[42:43]
	buffer_inv sc1
	s_waitcnt vmcnt(0)
	v_readfirstlane_b32 s4, v2
	s_nop 1
	v_add_u32_e32 v0, s4, v0
	v_and_b32_e32 v2, 3, v0
	v_cmp_ne_u32_e32 vcc, 3, v2
	s_and_saveexec_b64 s[40:41], vcc
	s_cbranch_execz .LBB0_906
	global_load_dword v2, v1, s[24:25] sc1
	v_bitop3_b32 v0, v0, -4, v0 bitop3:0xc
	s_waitcnt vmcnt(0)
	v_add_u32_e32 v2, v2, v0
	v_cmp_gt_i32_e32 vcc, 0, v2
	s_and_b64 exec, exec, vcc
	s_cbranch_execz .LBB0_906
	s_add_u32 s6, s6, 0x4200
	s_addc_u32 s7, s7, 0
	s_mov_b32 s4, 1
	s_mov_b64 s[42:43], 0
	s_branch .LBB0_895

.LBB0_998:
	s_or_b64 exec, exec, s[16:17]
	buffer_inv sc1
	s_waitcnt vmcnt(0)
	v_readfirstlane_b32 s2, v2
	s_nop 1
	v_add_u32_e32 v0, s2, v0
	v_and_b32_e32 v2, -4, v0
	v_and_b32_e32 v0, 3, v0
	v_cmp_eq_u32_e64 s[2:3], 3, v0
	v_add_u32_e32 v2, 4, v2
	s_and_b64 s[2:3], s[2:3], exec

.LBB0_1087:
	s_add_u32 s2, s6, 0x40080
	s_addc_u32 s3, s7, 0
	s_add_u32 s8, s8, 0x100
	s_addc_u32 s9, s9, 0
	s_mov_b32 s22, -2
	s_add_u32 s4, s2, 0xfffc0080
	s_addc_u32 s5, s3, -1
	s_add_i32 s23, 0, 0x10000
	s_cmp_eq_u32 s22, 12
	s_cselect_b32 s5, s49, s5
	s_cselect_b32 s4, s48, s4
	s_waitcnt vmcnt(0)
	v_add_u32_e32 v0, s23, v145
	s_cselect_b32 s7, s97, s9
	s_cselect_b32 s6, s96, s8
	s_add_i32 s25, 0, 0x14000
	ds_read_b128 v[146:149], v0
	ds_read_b128 v[152:155], v0 offset:1024
	ds_read_b128 v[156:159], v0 offset:2048
	ds_read_b128 v[160:163], v0 offset:3072
	v_add_u32_e32 v0, s25, v145
	ds_read_b128 v[164:167], v0
	ds_read_b128 v[168:171], v0 offset:1024
	ds_read_b128 v[172:175], v0 offset:2048
	ds_read_b128 v[176:179], v0 offset:3072
	v_mov_b32_e32 v0, v131
	ds_read_b128 v[180:183], v150
	ds_read_b128 v[184:187], v150 offset:1024
	ds_read_b128 v[188:191], v150 offset:2048
	ds_read_b128 v[192:195], v150 offset:3072
	ds_read_b128 v[196:199], v150 offset:4096
	ds_read_b128 v[200:203], v150 offset:5120
	ds_read_b128 v[204:207], v150 offset:6144
	ds_read_b128 v[208:211], v150 offset:7168
	s_add_i32 m0, s60, 0xc000
	s_nop 0
	global_load_lds_dwordx4 v0, s[2:3]
	v_mov_b32_e32 v0, v133
	s_add_i32 m0, s60, 0xe000
	s_nop 0
	global_load_lds_dwordx4 v0, s[2:3]
	s_waitcnt vmcnt(8)
	s_waitcnt lgkmcnt(0)
	s_barrier
	s_setprio 1
	s_waitcnt lgkmcnt(0)
	v_mfma_f32_16x16x32_bf16 v[126:129], v[146:149], v[180:183], 0
	v_mfma_f32_16x16x32_bf16 v[122:125], v[156:159], v[180:183], 0
	v_mfma_f32_16x16x32_bf16 v[110:113], v[146:149], v[188:191], 0
	v_mfma_f32_16x16x32_bf16 v[106:109], v[156:159], v[188:191], 0
	v_mfma_f32_16x16x32_bf16 v[94:97], v[146:149], v[196:199], 0
	v_mfma_f32_16x16x32_bf16 v[90:93], v[156:159], v[196:199], 0
	v_mfma_f32_16x16x32_bf16 v[78:81], v[146:149], v[204:207], 0
	v_mfma_f32_16x16x32_bf16 v[74:77], v[156:159], v[204:207], 0
	v_mfma_f32_16x16x32_bf16 v[126:129], v[152:155], v[184:187], v[126:129]
	v_mfma_f32_16x16x32_bf16 v[122:125], v[160:163], v[184:187], v[122:125]
	v_mfma_f32_16x16x32_bf16 v[110:113], v[152:155], v[192:195], v[110:113]
	v_mfma_f32_16x16x32_bf16 v[106:109], v[160:163], v[192:195], v[106:109]
	v_mfma_f32_16x16x32_bf16 v[94:97], v[152:155], v[200:203], v[94:97]
	v_mfma_f32_16x16x32_bf16 v[90:93], v[160:163], v[200:203], v[90:93]
	v_mfma_f32_16x16x32_bf16 v[78:81], v[152:155], v[208:211], v[78:81]
	v_mfma_f32_16x16x32_bf16 v[74:77], v[160:163], v[208:211], v[74:77]
	s_setprio 0
	s_setprio 1
	v_mfma_f32_16x16x32_bf16 v[118:121], v[164:167], v[180:183], 0
	v_mfma_f32_16x16x32_bf16 v[114:117], v[172:175], v[180:183], 0
	v_mfma_f32_16x16x32_bf16 v[102:105], v[164:167], v[188:191], 0
	v_mfma_f32_16x16x32_bf16 v[98:101], v[172:175], v[188:191], 0
	v_mfma_f32_16x16x32_bf16 v[86:89], v[164:167], v[196:199], 0
	v_mfma_f32_16x16x32_bf16 v[82:85], v[172:175], v[196:199], 0
	v_mfma_f32_16x16x32_bf16 v[70:73], v[164:167], v[204:207], 0
	v_mfma_f32_16x16x32_bf16 v[66:69], v[172:175], v[204:207], 0
	v_mfma_f32_16x16x32_bf16 v[118:121], v[168:171], v[184:187], v[118:121]
	v_mfma_f32_16x16x32_bf16 v[114:117], v[176:179], v[184:187], v[114:117]
	v_mfma_f32_16x16x32_bf16 v[102:105], v[168:171], v[192:195], v[102:105]
	v_mfma_f32_16x16x32_bf16 v[98:101], v[176:179], v[192:195], v[98:101]
	v_mfma_f32_16x16x32_bf16 v[86:89], v[168:171], v[200:203], v[86:89]
	v_mfma_f32_16x16x32_bf16 v[82:85], v[176:179], v[200:203], v[82:85]
	v_mfma_f32_16x16x32_bf16 v[70:73], v[168:171], v[208:211], v[70:73]
	v_mfma_f32_16x16x32_bf16 v[66:69], v[176:179], v[208:211], v[66:69]
	s_setprio 0
	s_barrier
	v_mov_b32_e32 v0, v137
	s_add_i32 s23, s23, s42
	ds_read_b128 v[180:183], v150 offset:16384
	ds_read_b128 v[184:187], v150 offset:17408
	ds_read_b128 v[188:191], v150 offset:18432
	ds_read_b128 v[192:195], v150 offset:19456
	ds_read_b128 v[196:199], v150 offset:20480
	ds_read_b128 v[200:203], v150 offset:21504
	ds_read_b128 v[204:207], v150 offset:22528
	ds_read_b128 v[208:211], v150 offset:23552
	s_mov_b32 m0, s23
	s_nop 0
	global_load_lds_dwordx4 v0, s[6:7]
	v_mov_b32_e32 v0, v139
	s_add_i32 m0, s23, 0x2000
	s_add_u32 s46, s6, 0x40000
	global_load_lds_dwordx4 v0, s[6:7]
	s_addc_u32 s47, s7, 0
	v_mov_b32_e32 v0, v137
	s_add_i32 s23, s25, s42
	s_mov_b32 m0, s23
	s_nop 0
	global_load_lds_dwordx4 v0, s[46:47]
	v_mov_b32_e32 v0, v139
	s_add_i32 m0, s23, 0x2000
	s_nop 0
	global_load_lds_dwordx4 v0, s[46:47]
	v_mov_b32_e32 v0, v131
	s_mov_b32 m0, s60
	s_nop 0
	global_load_lds_dwordx4 v0, s[4:5]
	v_mov_b32_e32 v0, v133
	s_mov_b32 m0, s61
	s_nop 0
	global_load_lds_dwordx4 v0, s[4:5]
	s_waitcnt vmcnt(8)
	s_waitcnt lgkmcnt(0)
	s_barrier
	s_setprio 1
	s_waitcnt lgkmcnt(0)
	v_mfma_f32_16x16x32_bf16 v[62:65], v[146:149], v[180:183], 0
	v_mfma_f32_16x16x32_bf16 v[58:61], v[156:159], v[180:183], 0
	v_mfma_f32_16x16x32_bf16 v[46:49], v[146:149], v[188:191], 0
	v_mfma_f32_16x16x32_bf16 v[42:45], v[156:159], v[188:191], 0
	v_mfma_f32_16x16x32_bf16 v[30:33], v[146:149], v[196:199], 0
	v_mfma_f32_16x16x32_bf16 v[26:29], v[156:159], v[196:199], 0
	v_mfma_f32_16x16x32_bf16 v[14:17], v[146:149], v[204:207], 0
	v_mfma_f32_16x16x32_bf16 v[10:13], v[156:159], v[204:207], 0
	v_mfma_f32_16x16x32_bf16 v[62:65], v[152:155], v[184:187], v[62:65]
	v_mfma_f32_16x16x32_bf16 v[58:61], v[160:163], v[184:187], v[58:61]
	v_mfma_f32_16x16x32_bf16 v[46:49], v[152:155], v[192:195], v[46:49]
	v_mfma_f32_16x16x32_bf16 v[42:45], v[160:163], v[192:195], v[42:45]
	v_mfma_f32_16x16x32_bf16 v[30:33], v[152:155], v[200:203], v[30:33]
	v_mfma_f32_16x16x32_bf16 v[26:29], v[160:163], v[200:203], v[26:29]
	v_mfma_f32_16x16x32_bf16 v[14:17], v[152:155], v[208:211], v[14:17]
	v_mfma_f32_16x16x32_bf16 v[10:13], v[160:163], v[208:211], v[10:13]
	s_setprio 0
	s_setprio 1
	v_mfma_f32_16x16x32_bf16 v[54:57], v[164:167], v[180:183], 0
	v_mfma_f32_16x16x32_bf16 v[50:53], v[172:175], v[180:183], 0
	v_mfma_f32_16x16x32_bf16 v[38:41], v[164:167], v[188:191], 0
	v_mfma_f32_16x16x32_bf16 v[34:37], v[172:175], v[188:191], 0
	v_mfma_f32_16x16x32_bf16 v[22:25], v[164:167], v[196:199], 0
	v_mfma_f32_16x16x32_bf16 v[18:21], v[172:175], v[196:199], 0
	v_mfma_f32_16x16x32_bf16 v[6:9], v[164:167], v[204:207], 0
	v_mfma_f32_16x16x32_bf16 v[2:5], v[172:175], v[204:207], 0
	v_mfma_f32_16x16x32_bf16 v[54:57], v[168:171], v[184:187], v[54:57]
	v_mfma_f32_16x16x32_bf16 v[50:53], v[176:179], v[184:187], v[50:53]
	v_mfma_f32_16x16x32_bf16 v[38:41], v[168:171], v[192:195], v[38:41]
	v_mfma_f32_16x16x32_bf16 v[34:37], v[176:179], v[192:195], v[34:37]
	v_mfma_f32_16x16x32_bf16 v[22:25], v[168:171], v[200:203], v[22:25]
	v_mfma_f32_16x16x32_bf16 v[18:21], v[176:179], v[200:203], v[18:21]
	v_mfma_f32_16x16x32_bf16 v[6:9], v[168:171], v[208:211], v[6:9]
	v_mfma_f32_16x16x32_bf16 v[2:5], v[176:179], v[208:211], v[2:5]
	s_setprio 0
	s_barrier
	s_add_i32 s23, 0, 0x18000
	v_add_u32_e32 v0, s23, v145
	s_add_i32 s25, 0, 0x1c000
	ds_read_b128 v[146:149], v0
	ds_read_b128 v[152:155], v0 offset:1024
	ds_read_b128 v[156:159], v0 offset:2048
	ds_read_b128 v[160:163], v0 offset:3072
	v_add_u32_e32 v0, s25, v145
	ds_read_b128 v[164:167], v0
	ds_read_b128 v[168:171], v0 offset:1024
	ds_read_b128 v[172:175], v0 offset:2048
	ds_read_b128 v[176:179], v0 offset:3072
	s_add_u32 s46, s4, 0x40000
	v_mov_b32_e32 v0, v131
	s_mov_b32 m0, s66
	ds_read_b128 v[180:183], v150 offset:32768
	ds_read_b128 v[184:187], v150 offset:33792
	ds_read_b128 v[188:191], v150 offset:34816
	ds_read_b128 v[192:195], v150 offset:35840
	ds_read_b128 v[196:199], v150 offset:36864
	ds_read_b128 v[200:203], v150 offset:37888
	ds_read_b128 v[204:207], v150 offset:38912
	ds_read_b128 v[208:211], v150 offset:39936
	s_addc_u32 s47, s5, 0
	s_nop 0
	global_load_lds_dwordx4 v0, s[46:47]
	v_mov_b32_e32 v0, v133
	s_mov_b32 m0, s67
	s_nop 0
	global_load_lds_dwordx4 v0, s[46:47]
	s_waitcnt vmcnt(8)
	s_waitcnt lgkmcnt(0)
	s_barrier
	s_setprio 1
	s_waitcnt lgkmcnt(0)
	v_mfma_f32_16x16x32_bf16 v[126:129], v[146:149], v[180:183], v[126:129]
	v_mfma_f32_16x16x32_bf16 v[122:125], v[156:159], v[180:183], v[122:125]
	v_mfma_f32_16x16x32_bf16 v[110:113], v[146:149], v[188:191], v[110:113]
	v_mfma_f32_16x16x32_bf16 v[106:109], v[156:159], v[188:191], v[106:109]
	v_mfma_f32_16x16x32_bf16 v[94:97], v[146:149], v[196:199], v[94:97]
	v_mfma_f32_16x16x32_bf16 v[90:93], v[156:159], v[196:199], v[90:93]
	v_mfma_f32_16x16x32_bf16 v[78:81], v[146:149], v[204:207], v[78:81]
	v_mfma_f32_16x16x32_bf16 v[74:77], v[156:159], v[204:207], v[74:77]
	v_mfma_f32_16x16x32_bf16 v[126:129], v[152:155], v[184:187], v[126:129]
	v_mfma_f32_16x16x32_bf16 v[122:125], v[160:163], v[184:187], v[122:125]
	v_mfma_f32_16x16x32_bf16 v[110:113], v[152:155], v[192:195], v[110:113]
	v_mfma_f32_16x16x32_bf16 v[106:109], v[160:163], v[192:195], v[106:109]
	v_mfma_f32_16x16x32_bf16 v[94:97], v[152:155], v[200:203], v[94:97]
	v_mfma_f32_16x16x32_bf16 v[90:93], v[160:163], v[200:203], v[90:93]
	v_mfma_f32_16x16x32_bf16 v[78:81], v[152:155], v[208:211], v[78:81]
	v_mfma_f32_16x16x32_bf16 v[74:77], v[160:163], v[208:211], v[74:77]
	s_setprio 0
	s_setprio 1
	v_mfma_f32_16x16x32_bf16 v[118:121], v[164:167], v[180:183], v[118:121]
	v_mfma_f32_16x16x32_bf16 v[114:117], v[172:175], v[180:183], v[114:117]
	v_mfma_f32_16x16x32_bf16 v[102:105], v[164:167], v[188:191], v[102:105]
	v_mfma_f32_16x16x32_bf16 v[98:101], v[172:175], v[188:191], v[98:101]
	v_mfma_f32_16x16x32_bf16 v[86:89], v[164:167], v[196:199], v[86:89]
	v_mfma_f32_16x16x32_bf16 v[82:85], v[172:175], v[196:199], v[82:85]
	v_mfma_f32_16x16x32_bf16 v[70:73], v[164:167], v[204:207], v[70:73]
	v_mfma_f32_16x16x32_bf16 v[66:69], v[172:175], v[204:207], v[66:69]
	v_mfma_f32_16x16x32_bf16 v[118:121], v[168:171], v[184:187], v[118:121]
	v_mfma_f32_16x16x32_bf16 v[114:117], v[176:179], v[184:187], v[114:117]
	v_mfma_f32_16x16x32_bf16 v[102:105], v[168:171], v[192:195], v[102:105]
	v_mfma_f32_16x16x32_bf16 v[98:101], v[176:179], v[192:195], v[98:101]
	v_mfma_f32_16x16x32_bf16 v[86:89], v[168:171], v[200:203], v[86:89]
	v_mfma_f32_16x16x32_bf16 v[82:85], v[176:179], v[200:203], v[82:85]
	v_mfma_f32_16x16x32_bf16 v[70:73], v[168:171], v[208:211], v[70:73]
	v_mfma_f32_16x16x32_bf16 v[66:69], v[176:179], v[208:211], v[66:69]
	s_setprio 0
	s_barrier
	v_mov_b32_e32 v0, v137
	ds_read_b128 v[180:183], v150 offset:49152
	ds_read_b128 v[184:187], v150 offset:50176
	ds_read_b128 v[188:191], v150 offset:51200
	ds_read_b128 v[192:195], v150 offset:52224
	ds_read_b128 v[196:199], v150 offset:53248
	ds_read_b128 v[200:203], v150 offset:54272
	ds_read_b128 v[204:207], v150 offset:55296
	ds_read_b128 v[208:211], v150 offset:56320
	s_add_i32 s23, s23, s42
	v_lshl_add_u64 v[212:213], s[6:7], 0, v[0:1]
	v_lshl_add_u64 v[212:213], v[212:213], 0, s[38:39]
	s_mov_b32 m0, s23
	v_mov_b32_e32 v0, v139
	global_load_lds_dwordx4 v[212:213], off
	s_add_i32 m0, s23, 0x2000
	s_nop 0
	v_lshl_add_u64 v[212:213], s[6:7], 0, v[0:1]
	s_add_u32 s6, s6, 0x40080
	v_lshl_add_u64 v[212:213], v[212:213], 0, s[38:39]
	s_addc_u32 s7, s7, 0
	v_mov_b32_e32 v0, v137
	s_add_i32 s23, s25, s42
	global_load_lds_dwordx4 v[212:213], off
	s_mov_b32 m0, s23
	s_nop 0
	global_load_lds_dwordx4 v0, s[6:7]
	v_mov_b32_e32 v0, v139
	s_add_i32 m0, s23, 0x2000
	s_nop 0
	global_load_lds_dwordx4 v0, s[6:7]
	v_mov_b32_e32 v0, v131
	s_mov_b32 m0, s70
	v_lshl_add_u64 v[212:213], s[4:5], 0, v[0:1]
	v_lshl_add_u64 v[212:213], v[212:213], 0, s[38:39]
	v_mov_b32_e32 v0, v133
	global_load_lds_dwordx4 v[212:213], off
	s_mov_b32 m0, s71
	v_lshl_add_u64 v[212:213], s[4:5], 0, v[0:1]
	v_lshl_add_u64 v[212:213], v[212:213], 0, s[38:39]
	global_load_lds_dwordx4 v[212:213], off
	s_waitcnt vmcnt(8)
	s_waitcnt lgkmcnt(0)
	s_barrier
	s_setprio 1
	s_waitcnt lgkmcnt(0)
	v_mfma_f32_16x16x32_bf16 v[62:65], v[146:149], v[180:183], v[62:65]
	v_mfma_f32_16x16x32_bf16 v[58:61], v[156:159], v[180:183], v[58:61]
	v_mfma_f32_16x16x32_bf16 v[46:49], v[146:149], v[188:191], v[46:49]
	v_mfma_f32_16x16x32_bf16 v[42:45], v[156:159], v[188:191], v[42:45]
	v_mfma_f32_16x16x32_bf16 v[30:33], v[146:149], v[196:199], v[30:33]
	v_mfma_f32_16x16x32_bf16 v[26:29], v[156:159], v[196:199], v[26:29]
	v_mfma_f32_16x16x32_bf16 v[14:17], v[146:149], v[204:207], v[14:17]
	v_mfma_f32_16x16x32_bf16 v[10:13], v[156:159], v[204:207], v[10:13]
	v_mfma_f32_16x16x32_bf16 v[62:65], v[152:155], v[184:187], v[62:65]
	v_mfma_f32_16x16x32_bf16 v[58:61], v[160:163], v[184:187], v[58:61]
	v_mfma_f32_16x16x32_bf16 v[46:49], v[152:155], v[192:195], v[46:49]
	v_mfma_f32_16x16x32_bf16 v[42:45], v[160:163], v[192:195], v[42:45]
	v_mfma_f32_16x16x32_bf16 v[30:33], v[152:155], v[200:203], v[30:33]
	v_mfma_f32_16x16x32_bf16 v[26:29], v[160:163], v[200:203], v[26:29]
	v_mfma_f32_16x16x32_bf16 v[14:17], v[152:155], v[208:211], v[14:17]
	v_mfma_f32_16x16x32_bf16 v[10:13], v[160:163], v[208:211], v[10:13]
	s_setprio 0
	s_setprio 1
	v_mfma_f32_16x16x32_bf16 v[54:57], v[164:167], v[180:183], v[54:57]
	v_mfma_f32_16x16x32_bf16 v[50:53], v[172:175], v[180:183], v[50:53]
	v_mfma_f32_16x16x32_bf16 v[38:41], v[164:167], v[188:191], v[38:41]
	v_mfma_f32_16x16x32_bf16 v[34:37], v[172:175], v[188:191], v[34:37]
	v_mfma_f32_16x16x32_bf16 v[22:25], v[164:167], v[196:199], v[22:25]
	v_mfma_f32_16x16x32_bf16 v[18:21], v[172:175], v[196:199], v[18:21]
	v_mfma_f32_16x16x32_bf16 v[6:9], v[164:167], v[204:207], v[6:9]
	v_mfma_f32_16x16x32_bf16 v[2:5], v[172:175], v[204:207], v[2:5]
	v_mfma_f32_16x16x32_bf16 v[54:57], v[168:171], v[184:187], v[54:57]
	v_mfma_f32_16x16x32_bf16 v[50:53], v[176:179], v[184:187], v[50:53]
	v_mfma_f32_16x16x32_bf16 v[38:41], v[168:171], v[192:195], v[38:41]
	v_mfma_f32_16x16x32_bf16 v[34:37], v[176:179], v[192:195], v[34:37]
	v_mfma_f32_16x16x32_bf16 v[22:25], v[168:171], v[200:203], v[22:25]
	v_mfma_f32_16x16x32_bf16 v[18:21], v[176:179], v[200:203], v[18:21]
	v_mfma_f32_16x16x32_bf16 v[6:9], v[168:171], v[208:211], v[6:9]
	v_mfma_f32_16x16x32_bf16 v[2:5], v[176:179], v[208:211], v[2:5]
	s_setprio 0
	s_barrier
	s_add_i32 s22, s22, 2
	s_add_u32 s2, s2, 0x100
	s_addc_u32 s3, s3, 0
	s_add_u32 s8, s8, 0x100
	s_addc_u32 s9, s9, 0
	s_cmp_gt_u32 s22, 13
	s_cbranch_scc0 .LBB0_1088
	s_branch .Lpeel_exit_1088
.LBB0_1088:
	s_add_u32 s4, s2, 0xfffc0080
	s_addc_u32 s5, s3, -1
	s_add_i32 s23, 0, 0x10000
	s_cmp_eq_u32 s22, 12
	s_cselect_b32 s5, s49, s5
	s_cselect_b32 s4, s48, s4
	v_add_u32_e32 v0, s23, v145
	s_cselect_b32 s7, s97, s9
	s_cselect_b32 s6, s96, s8
	s_add_i32 s25, 0, 0x14000
	ds_read_b128 v[146:149], v0
	ds_read_b128 v[152:155], v0 offset:1024
	ds_read_b128 v[156:159], v0 offset:2048
	ds_read_b128 v[160:163], v0 offset:3072
	v_add_u32_e32 v0, s25, v145
	ds_read_b128 v[164:167], v0
	ds_read_b128 v[168:171], v0 offset:1024
	ds_read_b128 v[172:175], v0 offset:2048
	ds_read_b128 v[176:179], v0 offset:3072
	v_mov_b32_e32 v0, v131
	ds_read_b128 v[180:183], v150
	ds_read_b128 v[184:187], v150 offset:1024
	ds_read_b128 v[188:191], v150 offset:2048
	ds_read_b128 v[192:195], v150 offset:3072
	ds_read_b128 v[196:199], v150 offset:4096
	ds_read_b128 v[200:203], v150 offset:5120
	ds_read_b128 v[204:207], v150 offset:6144
	ds_read_b128 v[208:211], v150 offset:7168
	s_add_i32 m0, s60, 0xc000
	s_nop 0
	global_load_lds_dwordx4 v0, s[2:3]
	v_mov_b32_e32 v0, v133
	s_add_i32 m0, s60, 0xe000
	s_nop 0
	global_load_lds_dwordx4 v0, s[2:3]
	s_waitcnt vmcnt(8)
	s_waitcnt lgkmcnt(0)
	s_barrier
	s_setprio 1
	s_waitcnt lgkmcnt(0)
	v_mfma_f32_16x16x32_bf16 v[126:129], v[146:149], v[180:183], v[126:129]
	v_mfma_f32_16x16x32_bf16 v[122:125], v[156:159], v[180:183], v[122:125]
	v_mfma_f32_16x16x32_bf16 v[110:113], v[146:149], v[188:191], v[110:113]
	v_mfma_f32_16x16x32_bf16 v[106:109], v[156:159], v[188:191], v[106:109]
	v_mfma_f32_16x16x32_bf16 v[94:97], v[146:149], v[196:199], v[94:97]
	v_mfma_f32_16x16x32_bf16 v[90:93], v[156:159], v[196:199], v[90:93]
	v_mfma_f32_16x16x32_bf16 v[78:81], v[146:149], v[204:207], v[78:81]
	v_mfma_f32_16x16x32_bf16 v[74:77], v[156:159], v[204:207], v[74:77]
	v_mfma_f32_16x16x32_bf16 v[126:129], v[152:155], v[184:187], v[126:129]
	v_mfma_f32_16x16x32_bf16 v[122:125], v[160:163], v[184:187], v[122:125]
	v_mfma_f32_16x16x32_bf16 v[110:113], v[152:155], v[192:195], v[110:113]
	v_mfma_f32_16x16x32_bf16 v[106:109], v[160:163], v[192:195], v[106:109]
	v_mfma_f32_16x16x32_bf16 v[94:97], v[152:155], v[200:203], v[94:97]
	v_mfma_f32_16x16x32_bf16 v[90:93], v[160:163], v[200:203], v[90:93]
	v_mfma_f32_16x16x32_bf16 v[78:81], v[152:155], v[208:211], v[78:81]
	v_mfma_f32_16x16x32_bf16 v[74:77], v[160:163], v[208:211], v[74:77]
	s_setprio 0
	s_setprio 1
	v_mfma_f32_16x16x32_bf16 v[118:121], v[164:167], v[180:183], v[118:121]
	v_mfma_f32_16x16x32_bf16 v[114:117], v[172:175], v[180:183], v[114:117]
	v_mfma_f32_16x16x32_bf16 v[102:105], v[164:167], v[188:191], v[102:105]
	v_mfma_f32_16x16x32_bf16 v[98:101], v[172:175], v[188:191], v[98:101]
	v_mfma_f32_16x16x32_bf16 v[86:89], v[164:167], v[196:199], v[86:89]
	v_mfma_f32_16x16x32_bf16 v[82:85], v[172:175], v[196:199], v[82:85]
	v_mfma_f32_16x16x32_bf16 v[70:73], v[164:167], v[204:207], v[70:73]
	v_mfma_f32_16x16x32_bf16 v[66:69], v[172:175], v[204:207], v[66:69]
	v_mfma_f32_16x16x32_bf16 v[118:121], v[168:171], v[184:187], v[118:121]
	v_mfma_f32_16x16x32_bf16 v[114:117], v[176:179], v[184:187], v[114:117]
	v_mfma_f32_16x16x32_bf16 v[102:105], v[168:171], v[192:195], v[102:105]
	v_mfma_f32_16x16x32_bf16 v[98:101], v[176:179], v[192:195], v[98:101]
	v_mfma_f32_16x16x32_bf16 v[86:89], v[168:171], v[200:203], v[86:89]
	v_mfma_f32_16x16x32_bf16 v[82:85], v[176:179], v[200:203], v[82:85]
	v_mfma_f32_16x16x32_bf16 v[70:73], v[168:171], v[208:211], v[70:73]
	v_mfma_f32_16x16x32_bf16 v[66:69], v[176:179], v[208:211], v[66:69]
	s_setprio 0
	s_barrier
	v_mov_b32_e32 v0, v137
	s_add_i32 s23, s23, s42
	ds_read_b128 v[180:183], v150 offset:16384
	ds_read_b128 v[184:187], v150 offset:17408
	ds_read_b128 v[188:191], v150 offset:18432
	ds_read_b128 v[192:195], v150 offset:19456
	ds_read_b128 v[196:199], v150 offset:20480
	ds_read_b128 v[200:203], v150 offset:21504
	ds_read_b128 v[204:207], v150 offset:22528
	ds_read_b128 v[208:211], v150 offset:23552
	s_mov_b32 m0, s23
	s_nop 0
	global_load_lds_dwordx4 v0, s[6:7]
	v_mov_b32_e32 v0, v139
	s_add_i32 m0, s23, 0x2000
	s_add_u32 s46, s6, 0x40000
	global_load_lds_dwordx4 v0, s[6:7]
	s_addc_u32 s47, s7, 0
	v_mov_b32_e32 v0, v137
	s_add_i32 s23, s25, s42
	s_mov_b32 m0, s23
	s_nop 0
	global_load_lds_dwordx4 v0, s[46:47]
	v_mov_b32_e32 v0, v139
	s_add_i32 m0, s23, 0x2000
	s_nop 0
	global_load_lds_dwordx4 v0, s[46:47]
	v_mov_b32_e32 v0, v131
	s_mov_b32 m0, s60
	s_nop 0
	global_load_lds_dwordx4 v0, s[4:5]
	v_mov_b32_e32 v0, v133
	s_mov_b32 m0, s61
	s_nop 0
	global_load_lds_dwordx4 v0, s[4:5]
	s_waitcnt vmcnt(8)
	s_waitcnt lgkmcnt(0)
	s_barrier
	s_setprio 1
	s_waitcnt lgkmcnt(0)
	v_mfma_f32_16x16x32_bf16 v[62:65], v[146:149], v[180:183], v[62:65]
	v_mfma_f32_16x16x32_bf16 v[58:61], v[156:159], v[180:183], v[58:61]
	v_mfma_f32_16x16x32_bf16 v[46:49], v[146:149], v[188:191], v[46:49]
	v_mfma_f32_16x16x32_bf16 v[42:45], v[156:159], v[188:191], v[42:45]
	v_mfma_f32_16x16x32_bf16 v[30:33], v[146:149], v[196:199], v[30:33]
	v_mfma_f32_16x16x32_bf16 v[26:29], v[156:159], v[196:199], v[26:29]
	v_mfma_f32_16x16x32_bf16 v[14:17], v[146:149], v[204:207], v[14:17]
	v_mfma_f32_16x16x32_bf16 v[10:13], v[156:159], v[204:207], v[10:13]
	v_mfma_f32_16x16x32_bf16 v[62:65], v[152:155], v[184:187], v[62:65]
	v_mfma_f32_16x16x32_bf16 v[58:61], v[160:163], v[184:187], v[58:61]
	v_mfma_f32_16x16x32_bf16 v[46:49], v[152:155], v[192:195], v[46:49]
	v_mfma_f32_16x16x32_bf16 v[42:45], v[160:163], v[192:195], v[42:45]
	v_mfma_f32_16x16x32_bf16 v[30:33], v[152:155], v[200:203], v[30:33]
	v_mfma_f32_16x16x32_bf16 v[26:29], v[160:163], v[200:203], v[26:29]
	v_mfma_f32_16x16x32_bf16 v[14:17], v[152:155], v[208:211], v[14:17]
	v_mfma_f32_16x16x32_bf16 v[10:13], v[160:163], v[208:211], v[10:13]
	s_setprio 0
	s_setprio 1
	v_mfma_f32_16x16x32_bf16 v[54:57], v[164:167], v[180:183], v[54:57]
	v_mfma_f32_16x16x32_bf16 v[50:53], v[172:175], v[180:183], v[50:53]
	v_mfma_f32_16x16x32_bf16 v[38:41], v[164:167], v[188:191], v[38:41]
	v_mfma_f32_16x16x32_bf16 v[34:37], v[172:175], v[188:191], v[34:37]
	v_mfma_f32_16x16x32_bf16 v[22:25], v[164:167], v[196:199], v[22:25]
	v_mfma_f32_16x16x32_bf16 v[18:21], v[172:175], v[196:199], v[18:21]
	v_mfma_f32_16x16x32_bf16 v[6:9], v[164:167], v[204:207], v[6:9]
	v_mfma_f32_16x16x32_bf16 v[2:5], v[172:175], v[204:207], v[2:5]
	v_mfma_f32_16x16x32_bf16 v[54:57], v[168:171], v[184:187], v[54:57]
	v_mfma_f32_16x16x32_bf16 v[50:53], v[176:179], v[184:187], v[50:53]
	v_mfma_f32_16x16x32_bf16 v[38:41], v[168:171], v[192:195], v[38:41]
	v_mfma_f32_16x16x32_bf16 v[34:37], v[176:179], v[192:195], v[34:37]
	v_mfma_f32_16x16x32_bf16 v[22:25], v[168:171], v[200:203], v[22:25]
	v_mfma_f32_16x16x32_bf16 v[18:21], v[176:179], v[200:203], v[18:21]
	v_mfma_f32_16x16x32_bf16 v[6:9], v[168:171], v[208:211], v[6:9]
	v_mfma_f32_16x16x32_bf16 v[2:5], v[176:179], v[208:211], v[2:5]
	s_setprio 0
	s_barrier
	s_add_i32 s23, 0, 0x18000
	v_add_u32_e32 v0, s23, v145
	s_add_i32 s25, 0, 0x1c000
	ds_read_b128 v[146:149], v0
	ds_read_b128 v[152:155], v0 offset:1024
	ds_read_b128 v[156:159], v0 offset:2048
	ds_read_b128 v[160:163], v0 offset:3072
	v_add_u32_e32 v0, s25, v145
	ds_read_b128 v[164:167], v0
	ds_read_b128 v[168:171], v0 offset:1024
	ds_read_b128 v[172:175], v0 offset:2048
	ds_read_b128 v[176:179], v0 offset:3072
	s_add_u32 s46, s4, 0x40000
	v_mov_b32_e32 v0, v131
	s_mov_b32 m0, s66
	ds_read_b128 v[180:183], v150 offset:32768
	ds_read_b128 v[184:187], v150 offset:33792
	ds_read_b128 v[188:191], v150 offset:34816
	ds_read_b128 v[192:195], v150 offset:35840
	ds_read_b128 v[196:199], v150 offset:36864
	ds_read_b128 v[200:203], v150 offset:37888
	ds_read_b128 v[204:207], v150 offset:38912
	ds_read_b128 v[208:211], v150 offset:39936
	s_addc_u32 s47, s5, 0
	s_nop 0
	global_load_lds_dwordx4 v0, s[46:47]
	v_mov_b32_e32 v0, v133
	s_mov_b32 m0, s67
	s_nop 0
	global_load_lds_dwordx4 v0, s[46:47]
	s_waitcnt vmcnt(8)
	s_waitcnt lgkmcnt(0)
	s_barrier
	s_setprio 1
	s_waitcnt lgkmcnt(0)
	v_mfma_f32_16x16x32_bf16 v[126:129], v[146:149], v[180:183], v[126:129]
	v_mfma_f32_16x16x32_bf16 v[122:125], v[156:159], v[180:183], v[122:125]
	v_mfma_f32_16x16x32_bf16 v[110:113], v[146:149], v[188:191], v[110:113]
	v_mfma_f32_16x16x32_bf16 v[106:109], v[156:159], v[188:191], v[106:109]
	v_mfma_f32_16x16x32_bf16 v[94:97], v[146:149], v[196:199], v[94:97]
	v_mfma_f32_16x16x32_bf16 v[90:93], v[156:159], v[196:199], v[90:93]
	v_mfma_f32_16x16x32_bf16 v[78:81], v[146:149], v[204:207], v[78:81]
	v_mfma_f32_16x16x32_bf16 v[74:77], v[156:159], v[204:207], v[74:77]
	v_mfma_f32_16x16x32_bf16 v[126:129], v[152:155], v[184:187], v[126:129]
	v_mfma_f32_16x16x32_bf16 v[122:125], v[160:163], v[184:187], v[122:125]
	v_mfma_f32_16x16x32_bf16 v[110:113], v[152:155], v[192:195], v[110:113]
	v_mfma_f32_16x16x32_bf16 v[106:109], v[160:163], v[192:195], v[106:109]
	v_mfma_f32_16x16x32_bf16 v[94:97], v[152:155], v[200:203], v[94:97]
	v_mfma_f32_16x16x32_bf16 v[90:93], v[160:163], v[200:203], v[90:93]
	v_mfma_f32_16x16x32_bf16 v[78:81], v[152:155], v[208:211], v[78:81]
	v_mfma_f32_16x16x32_bf16 v[74:77], v[160:163], v[208:211], v[74:77]
	s_setprio 0
	s_setprio 1
	v_mfma_f32_16x16x32_bf16 v[118:121], v[164:167], v[180:183], v[118:121]
	v_mfma_f32_16x16x32_bf16 v[114:117], v[172:175], v[180:183], v[114:117]
	v_mfma_f32_16x16x32_bf16 v[102:105], v[164:167], v[188:191], v[102:105]
	v_mfma_f32_16x16x32_bf16 v[98:101], v[172:175], v[188:191], v[98:101]
	v_mfma_f32_16x16x32_bf16 v[86:89], v[164:167], v[196:199], v[86:89]
	v_mfma_f32_16x16x32_bf16 v[82:85], v[172:175], v[196:199], v[82:85]
	v_mfma_f32_16x16x32_bf16 v[70:73], v[164:167], v[204:207], v[70:73]
	v_mfma_f32_16x16x32_bf16 v[66:69], v[172:175], v[204:207], v[66:69]
	v_mfma_f32_16x16x32_bf16 v[118:121], v[168:171], v[184:187], v[118:121]
	v_mfma_f32_16x16x32_bf16 v[114:117], v[176:179], v[184:187], v[114:117]
	v_mfma_f32_16x16x32_bf16 v[102:105], v[168:171], v[192:195], v[102:105]
	v_mfma_f32_16x16x32_bf16 v[98:101], v[176:179], v[192:195], v[98:101]
	v_mfma_f32_16x16x32_bf16 v[86:89], v[168:171], v[200:203], v[86:89]
	v_mfma_f32_16x16x32_bf16 v[82:85], v[176:179], v[200:203], v[82:85]
	v_mfma_f32_16x16x32_bf16 v[70:73], v[168:171], v[208:211], v[70:73]
	v_mfma_f32_16x16x32_bf16 v[66:69], v[176:179], v[208:211], v[66:69]
	s_setprio 0
	s_barrier
	v_mov_b32_e32 v0, v137
	ds_read_b128 v[180:183], v150 offset:49152
	ds_read_b128 v[184:187], v150 offset:50176
	ds_read_b128 v[188:191], v150 offset:51200
	ds_read_b128 v[192:195], v150 offset:52224
	ds_read_b128 v[196:199], v150 offset:53248
	ds_read_b128 v[200:203], v150 offset:54272
	ds_read_b128 v[204:207], v150 offset:55296
	ds_read_b128 v[208:211], v150 offset:56320
	s_add_i32 s23, s23, s42
	v_lshl_add_u64 v[212:213], s[6:7], 0, v[0:1]
	v_lshl_add_u64 v[212:213], v[212:213], 0, s[38:39]
	s_mov_b32 m0, s23
	v_mov_b32_e32 v0, v139
	global_load_lds_dwordx4 v[212:213], off
	s_add_i32 m0, s23, 0x2000
	s_nop 0
	v_lshl_add_u64 v[212:213], s[6:7], 0, v[0:1]
	s_add_u32 s6, s6, 0x40080
	v_lshl_add_u64 v[212:213], v[212:213], 0, s[38:39]
	s_addc_u32 s7, s7, 0
	v_mov_b32_e32 v0, v137
	s_add_i32 s23, s25, s42
	global_load_lds_dwordx4 v[212:213], off
	s_mov_b32 m0, s23
	s_nop 0
	global_load_lds_dwordx4 v0, s[6:7]
	v_mov_b32_e32 v0, v139
	s_add_i32 m0, s23, 0x2000
	s_nop 0
	global_load_lds_dwordx4 v0, s[6:7]
	v_mov_b32_e32 v0, v131
	s_mov_b32 m0, s70
	v_lshl_add_u64 v[212:213], s[4:5], 0, v[0:1]
	v_lshl_add_u64 v[212:213], v[212:213], 0, s[38:39]
	v_mov_b32_e32 v0, v133
	global_load_lds_dwordx4 v[212:213], off
	s_mov_b32 m0, s71
	v_lshl_add_u64 v[212:213], s[4:5], 0, v[0:1]
	v_lshl_add_u64 v[212:213], v[212:213], 0, s[38:39]
	global_load_lds_dwordx4 v[212:213], off
	s_waitcnt vmcnt(8)
	s_waitcnt lgkmcnt(0)
	s_barrier
	s_setprio 1
	s_waitcnt lgkmcnt(0)
	v_mfma_f32_16x16x32_bf16 v[62:65], v[146:149], v[180:183], v[62:65]
	v_mfma_f32_16x16x32_bf16 v[58:61], v[156:159], v[180:183], v[58:61]
	v_mfma_f32_16x16x32_bf16 v[46:49], v[146:149], v[188:191], v[46:49]
	v_mfma_f32_16x16x32_bf16 v[42:45], v[156:159], v[188:191], v[42:45]
	v_mfma_f32_16x16x32_bf16 v[30:33], v[146:149], v[196:199], v[30:33]
	v_mfma_f32_16x16x32_bf16 v[26:29], v[156:159], v[196:199], v[26:29]
	v_mfma_f32_16x16x32_bf16 v[14:17], v[146:149], v[204:207], v[14:17]
	v_mfma_f32_16x16x32_bf16 v[10:13], v[156:159], v[204:207], v[10:13]
	v_mfma_f32_16x16x32_bf16 v[62:65], v[152:155], v[184:187], v[62:65]
	v_mfma_f32_16x16x32_bf16 v[58:61], v[160:163], v[184:187], v[58:61]
	v_mfma_f32_16x16x32_bf16 v[46:49], v[152:155], v[192:195], v[46:49]
	v_mfma_f32_16x16x32_bf16 v[42:45], v[160:163], v[192:195], v[42:45]
	v_mfma_f32_16x16x32_bf16 v[30:33], v[152:155], v[200:203], v[30:33]
	v_mfma_f32_16x16x32_bf16 v[26:29], v[160:163], v[200:203], v[26:29]
	v_mfma_f32_16x16x32_bf16 v[14:17], v[152:155], v[208:211], v[14:17]
	v_mfma_f32_16x16x32_bf16 v[10:13], v[160:163], v[208:211], v[10:13]
	s_setprio 0
	s_setprio 1
	v_mfma_f32_16x16x32_bf16 v[54:57], v[164:167], v[180:183], v[54:57]
	v_mfma_f32_16x16x32_bf16 v[50:53], v[172:175], v[180:183], v[50:53]
	v_mfma_f32_16x16x32_bf16 v[38:41], v[164:167], v[188:191], v[38:41]
	v_mfma_f32_16x16x32_bf16 v[34:37], v[172:175], v[188:191], v[34:37]
	v_mfma_f32_16x16x32_bf16 v[22:25], v[164:167], v[196:199], v[22:25]
	v_mfma_f32_16x16x32_bf16 v[18:21], v[172:175], v[196:199], v[18:21]
	v_mfma_f32_16x16x32_bf16 v[6:9], v[164:167], v[204:207], v[6:9]
	v_mfma_f32_16x16x32_bf16 v[2:5], v[172:175], v[204:207], v[2:5]
	v_mfma_f32_16x16x32_bf16 v[54:57], v[168:171], v[184:187], v[54:57]
	v_mfma_f32_16x16x32_bf16 v[50:53], v[176:179], v[184:187], v[50:53]
	v_mfma_f32_16x16x32_bf16 v[38:41], v[168:171], v[192:195], v[38:41]
	v_mfma_f32_16x16x32_bf16 v[34:37], v[176:179], v[192:195], v[34:37]
	v_mfma_f32_16x16x32_bf16 v[22:25], v[168:171], v[200:203], v[22:25]
	v_mfma_f32_16x16x32_bf16 v[18:21], v[176:179], v[200:203], v[18:21]
	v_mfma_f32_16x16x32_bf16 v[6:9], v[168:171], v[208:211], v[6:9]
	v_mfma_f32_16x16x32_bf16 v[2:5], v[176:179], v[208:211], v[2:5]
	s_setprio 0
	s_barrier
	s_add_i32 s22, s22, 2
	s_add_u32 s2, s2, 0x100
	s_addc_u32 s3, s3, 0
	s_add_u32 s8, s8, 0x100
	s_addc_u32 s9, s9, 0
	s_cmp_gt_u32 s22, 13
	s_cbranch_scc0 .LBB0_1088
.Lpeel_exit_1088:
	s_and_b64 vcc, exec, s[16:17]
	s_cbranch_vccz .LBB0_1091
	s_barrier

.LBB0_1223:
	s_or_b64 exec, exec, s[10:11]
	buffer_inv sc1
	s_waitcnt vmcnt(0)
	v_readfirstlane_b32 s6, v2
	s_nop 1
	v_add_u32_e32 v0, s6, v0
	v_and_b32_e32 v2, 31, v0
	v_cmp_ne_u32_e32 vcc, 31, v2
	s_and_saveexec_b64 s[6:7], vcc
	s_cbranch_execz .LBB0_1237
	global_load_dword v2, v1, s[4:5] sc1
	s_movk_i32 s10, 0xffe0
	v_bitop3_b32 v0, v0, s10, v0 bitop3:0xc
	s_waitcnt vmcnt(0)
	v_add_u32_e32 v2, v2, v0
	v_cmp_gt_i32_e32 vcc, 0, v2
	s_and_b64 exec, exec, vcc
	s_cbranch_execz .LBB0_1237
	s_add_u32 s8, s8, 0x4200
	s_addc_u32 s9, s9, 0
	s_mov_b32 s24, 1
	s_mov_b64 s[10:11], 0
	s_branch .LBB0_1227

.LBB0_1489:
	s_or_b64 exec, exec, s[16:17]
	buffer_inv sc1
	s_waitcnt vmcnt(0)
	v_readfirstlane_b32 s2, v2
	s_nop 1
	v_add_u32_e32 v0, s2, v0
	v_and_b32_e32 v2, 0xffffffe0, v0
	v_and_b32_e32 v0, 31, v0
	v_cmp_eq_u32_e64 s[2:3], 31, v0
	v_add_u32_e32 v2, 32, v2
	s_and_b64 s[2:3], s[2:3], exec

.LBB0_1723:
	s_or_b64 exec, exec, s[22:23]
	buffer_inv sc1
	s_waitcnt vmcnt(0)
	v_readfirstlane_b32 s2, v2
	s_nop 1
	v_add_u32_e32 v0, s2, v0
	v_and_b32_e32 v2, -4, v0
	v_and_b32_e32 v0, 3, v0
	v_cmp_eq_u32_e64 s[2:3], 3, v0
	v_add_u32_e32 v2, 4, v2
	s_and_b64 s[2:3], s[2:3], exec

.LBB0_1829:
	s_or_b64 exec, exec, s[40:41]
	buffer_inv sc1
	s_waitcnt vmcnt(0)
	v_readfirstlane_b32 s24, v2
	s_nop 1
	v_add_u32_e32 v0, s24, v0
	v_and_b32_e32 v2, 3, v0
	v_cmp_ne_u32_e32 vcc, 3, v2
	s_and_saveexec_b64 s[24:25], vcc
	s_cbranch_execz .LBB0_1843
	global_load_dword v2, v1, s[22:23] sc1
	v_bitop3_b32 v0, v0, -4, v0 bitop3:0xc
	s_waitcnt vmcnt(0)
	v_add_u32_e32 v2, v2, v0
	v_cmp_gt_i32_e32 vcc, 0, v2
	s_and_b64 exec, exec, vcc
	s_cbranch_execz .LBB0_1843
	s_add_u32 s6, s6, 0x4200
	s_addc_u32 s7, s7, 0
	s_mov_b32 s26, 1
	s_mov_b64 s[40:41], 0
	s_branch .LBB0_1833

.LBB0_1911:
	s_or_b64 exec, exec, s[10:11]
	buffer_inv sc1
	s_waitcnt vmcnt(0)
	v_readfirstlane_b32 s6, v2
	s_nop 1
	v_add_u32_e32 v0, s6, v0
	v_and_b32_e32 v2, 3, v0
	v_cmp_ne_u32_e32 vcc, 3, v2
	s_and_saveexec_b64 s[6:7], vcc
	s_cbranch_execz .LBB0_1925
	global_load_dword v2, v1, s[4:5] sc1
	v_bitop3_b32 v0, v0, -4, v0 bitop3:0xc
	s_waitcnt vmcnt(0)
	v_add_u32_e32 v2, v2, v0
	v_cmp_gt_i32_e32 vcc, 0, v2
	s_and_b64 exec, exec, vcc
	s_cbranch_execz .LBB0_1925
	s_add_u32 s8, s8, 0x4200
	s_addc_u32 s9, s9, 0
	s_mov_b32 s24, 1
	s_mov_b64 s[10:11], 0
	s_branch .LBB0_1915
